# stack: mout sample intra V loads hoisted after q.k^T chain, on top of sample attention remap + sample epilogue/mstate hoists
# speedup vs baseline: 1.0043x; 1.0008x over previous
; #define MFMA32(a, b, c) __builtin_amdgcn_mfma_f32_32x32x16_bf16((a), (b), (c), 0, 0, 0)
; __device__ __forceinline__ s16x8 pack8(const float (&x)[8]) { u32x4 p; p.x = pk2(x[0], x[1]); p.y = pk2(x[2], x[3]); p.z = pk2(x[4], x[5]); p.w = pk2(x[6], x[7]); return __builtin_bit_cast(s16x8, p); }
; template <bool SAMPLE>
; __device__ __forceinline__ void mout_task(Ctx& C, int l, int unit, int h, int tb, const LAS float* cwl, const LAS float* gainl, LAS float* gsbuf, LAS s16x8* qfl, const bool st) {
;     ...
;         const float* cp = C.in[5] + ((size_t)l * NSLOT_S + unit * 4 + h) * 16384 + r;
; #pragma unroll 1
;         for (int ks = 0; ks < 8; ++ks) { const s16x8 qv = qfl[ks * 64 + lane];
; #pragma unroll
;             for (int vb = 0; vb < 4; ++vb) { float x[8];
; #pragma unroll
;                 for (int e = 0; e < 8; ++e) x[e] = cp[(size_t)(16 * ks + 8 * hi + e) * 128 + 32 * vb];
;                 acc[vb] = MFMA32(pack8(x), qv, acc[vb]); } }
.LBB0_920:
	global_load_dword v132, v[36:37], off offset:-2048
	global_load_dword v133, v[36:37], off offset:-1536
	global_load_dword v134, v[36:37], off offset:-1024
	global_load_dword v135, v[36:37], off offset:-512
	global_load_dword v136, v[36:37], off
	global_load_dword v137, v[36:37], off offset:512
	global_load_dword v138, v[36:37], off offset:1024
	global_load_dword v139, v[36:37], off offset:1536
	global_load_dword v140, v[36:37], off offset:-1920
	global_load_dword v141, v[36:37], off offset:-1408
	global_load_dword v142, v[36:37], off offset:-896
	global_load_dword v143, v[36:37], off offset:-384
	global_load_dword v144, v[36:37], off offset:128
	global_load_dword v145, v[36:37], off offset:640
	global_load_dword v146, v[36:37], off offset:1152
	global_load_dword v147, v[36:37], off offset:1664
	global_load_dword v148, v[36:37], off offset:-1792
	global_load_dword v149, v[36:37], off offset:-1280
	global_load_dword v150, v[36:37], off offset:-768
	global_load_dword v151, v[36:37], off offset:-256
	global_load_dword v152, v[36:37], off offset:256
	global_load_dword v153, v[36:37], off offset:768
	global_load_dword v154, v[36:37], off offset:1280
	global_load_dword v155, v[36:37], off offset:1792
	global_load_dword v156, v[36:37], off offset:-1664
	global_load_dword v157, v[36:37], off offset:-1152
	global_load_dword v158, v[36:37], off offset:-640
	global_load_dword v159, v[36:37], off offset:-128
	global_load_dword v160, v[36:37], off offset:384
	global_load_dword v161, v[36:37], off offset:896
	global_load_dword v162, v[36:37], off offset:1408
	global_load_dword v163, v[36:37], off offset:1920
	v_lshl_add_u64 v[36:37], v[36:37], 0, s[28:29]
	global_load_dword v164, v[36:37], off offset:-2048
	global_load_dword v165, v[36:37], off offset:-1536
	global_load_dword v166, v[36:37], off offset:-1024
	global_load_dword v167, v[36:37], off offset:-512
	global_load_dword v168, v[36:37], off
	global_load_dword v169, v[36:37], off offset:512
	global_load_dword v170, v[36:37], off offset:1024
	global_load_dword v171, v[36:37], off offset:1536
	global_load_dword v172, v[36:37], off offset:-1920
	global_load_dword v173, v[36:37], off offset:-1408
	global_load_dword v174, v[36:37], off offset:-896
	global_load_dword v175, v[36:37], off offset:-384
	global_load_dword v176, v[36:37], off offset:128
	global_load_dword v177, v[36:37], off offset:640
	global_load_dword v178, v[36:37], off offset:1152
	global_load_dword v179, v[36:37], off offset:1664
	global_load_dword v180, v[36:37], off offset:-1792
	global_load_dword v181, v[36:37], off offset:-1280
	global_load_dword v182, v[36:37], off offset:-768
	global_load_dword v183, v[36:37], off offset:-256
	global_load_dword v184, v[36:37], off offset:256
	global_load_dword v47, v[36:37], off offset:768
	global_load_dword v48, v[36:37], off offset:1280
	global_load_dword v49, v[36:37], off offset:1792
	global_load_dword v50, v[36:37], off offset:-1664
	global_load_dword v51, v[36:37], off offset:-1152
	global_load_dword v52, v[36:37], off offset:-640
	global_load_dword v53, v[36:37], off offset:-128
	global_load_dword v54, v[36:37], off offset:384
	global_load_dword v55, v[36:37], off offset:896
	global_load_dword v56, v[36:37], off offset:1408
	global_load_dword v57, v[36:37], off offset:1920
	v_lshl_add_u64 v[36:37], v[36:37], 0, s[28:29]
	ds_read_b128 v[32:35], v131
	ds_read_b128 v[104:107], v131 offset:1024
	s_waitcnt vmcnt(56) lgkmcnt(1)
	v_cvt_pk_bf16_f32 v40, v132, v133
	v_cvt_pk_bf16_f32 v41, v134, v135
	v_cvt_pk_bf16_f32 v42, v136, v137
	v_cvt_pk_bf16_f32 v43, v138, v139
	global_load_dword v132, v[36:37], off offset:-2048
	global_load_dword v133, v[36:37], off offset:-1536
	global_load_dword v134, v[36:37], off offset:-1024
	global_load_dword v135, v[36:37], off offset:-512
	global_load_dword v136, v[36:37], off
	global_load_dword v137, v[36:37], off offset:512
	global_load_dword v138, v[36:37], off offset:1024
	global_load_dword v139, v[36:37], off offset:1536
	v_mfma_f32_32x32x16_bf16 v[0:15], v[40:43], v[32:35], v[0:15]
	s_waitcnt vmcnt(56)
	v_cvt_pk_bf16_f32 v60, v140, v141
	v_cvt_pk_bf16_f32 v61, v142, v143
	v_cvt_pk_bf16_f32 v62, v144, v145
	v_cvt_pk_bf16_f32 v63, v146, v147
	global_load_dword v140, v[36:37], off offset:-1920
	global_load_dword v141, v[36:37], off offset:-1408
	global_load_dword v142, v[36:37], off offset:-896
	global_load_dword v143, v[36:37], off offset:-384
	global_load_dword v144, v[36:37], off offset:128
	global_load_dword v145, v[36:37], off offset:640
	global_load_dword v146, v[36:37], off offset:1152
	global_load_dword v147, v[36:37], off offset:1664
	v_mfma_f32_32x32x16_bf16 v[16:31], v[60:63], v[32:35], v[16:31]
	s_waitcnt vmcnt(56)
	v_cvt_pk_bf16_f32 v40, v148, v149
	v_cvt_pk_bf16_f32 v41, v150, v151
	v_cvt_pk_bf16_f32 v42, v152, v153
	v_cvt_pk_bf16_f32 v43, v154, v155
	global_load_dword v148, v[36:37], off offset:-1792
	global_load_dword v149, v[36:37], off offset:-1280
	global_load_dword v150, v[36:37], off offset:-768
	global_load_dword v151, v[36:37], off offset:-256
	global_load_dword v152, v[36:37], off offset:256
	global_load_dword v153, v[36:37], off offset:768
	global_load_dword v154, v[36:37], off offset:1280
	global_load_dword v155, v[36:37], off offset:1792
	v_mfma_f32_32x32x16_bf16 v[64:79], v[40:43], v[32:35], v[64:79]
	s_waitcnt vmcnt(56)
; #define MFMA32(a, b, c) __builtin_amdgcn_mfma_f32_32x32x16_bf16((a), (b), (c), 0, 0, 0)
; __device__ __forceinline__ s16x8 pack8(const float (&x)[8]) { u32x4 p; p.x = pk2(x[0], x[1]); p.y = pk2(x[2], x[3]); p.z = pk2(x[4], x[5]); p.w = pk2(x[6], x[7]); return __builtin_bit_cast(s16x8, p); }
; template <bool SAMPLE>
; __device__ __forceinline__ void mout_task(Ctx& C, int l, int unit, int h, int tb, const LAS float* cwl, const LAS float* gainl, LAS float* gsbuf, LAS s16x8* qfl, const bool st) {
;     ...
;         for (int ks = 0; ks < 8; ++ks) { const s16x8 qv = qfl[ks * 64 + lane];
; #pragma unroll
;             for (int vb = 0; vb < 4; ++vb) { float x[8];
; #pragma unroll
;                 for (int e = 0; e < 8; ++e) x[e] = cp[(size_t)(16 * ks + 8 * hi + e) * 128 + 32 * vb];
;                 acc[vb] = MFMA32(pack8(x), qv, acc[vb]); } }
	v_cvt_pk_bf16_f32 v60, v156, v157
	v_cvt_pk_bf16_f32 v61, v158, v159
	v_cvt_pk_bf16_f32 v62, v160, v161
	v_cvt_pk_bf16_f32 v63, v162, v163
	global_load_dword v156, v[36:37], off offset:-1664
	global_load_dword v157, v[36:37], off offset:-1152
	global_load_dword v158, v[36:37], off offset:-640
	global_load_dword v159, v[36:37], off offset:-128
	global_load_dword v160, v[36:37], off offset:384
	global_load_dword v161, v[36:37], off offset:896
	global_load_dword v162, v[36:37], off offset:1408
	global_load_dword v163, v[36:37], off offset:1920
	v_mfma_f32_32x32x16_bf16 v[80:95], v[60:63], v[32:35], v[80:95]
	v_lshl_add_u64 v[36:37], v[36:37], 0, s[28:29]
	ds_read_b128 v[32:35], v131 offset:2048
	s_waitcnt vmcnt(56) lgkmcnt(1)
	v_cvt_pk_bf16_f32 v40, v164, v165
	v_cvt_pk_bf16_f32 v41, v166, v167
	v_cvt_pk_bf16_f32 v42, v168, v169
	v_cvt_pk_bf16_f32 v43, v170, v171
	global_load_dword v164, v[36:37], off offset:-2048
	global_load_dword v165, v[36:37], off offset:-1536
	global_load_dword v166, v[36:37], off offset:-1024
	global_load_dword v167, v[36:37], off offset:-512
	global_load_dword v168, v[36:37], off
	global_load_dword v169, v[36:37], off offset:512
	global_load_dword v170, v[36:37], off offset:1024
	global_load_dword v171, v[36:37], off offset:1536
	v_mfma_f32_32x32x16_bf16 v[0:15], v[40:43], v[104:107], v[0:15]
	s_waitcnt vmcnt(56)
	v_cvt_pk_bf16_f32 v60, v172, v173
	v_cvt_pk_bf16_f32 v61, v174, v175
	v_cvt_pk_bf16_f32 v62, v176, v177
	v_cvt_pk_bf16_f32 v63, v178, v179
	global_load_dword v172, v[36:37], off offset:-1920
	global_load_dword v173, v[36:37], off offset:-1408
	global_load_dword v174, v[36:37], off offset:-896
	global_load_dword v175, v[36:37], off offset:-384
	global_load_dword v176, v[36:37], off offset:128
	global_load_dword v177, v[36:37], off offset:640
	global_load_dword v178, v[36:37], off offset:1152
	global_load_dword v179, v[36:37], off offset:1664
	v_mfma_f32_32x32x16_bf16 v[16:31], v[60:63], v[104:107], v[16:31]
	s_waitcnt vmcnt(56)
	v_cvt_pk_bf16_f32 v40, v180, v181
	v_cvt_pk_bf16_f32 v41, v182, v183
	v_cvt_pk_bf16_f32 v42, v184, v47
	v_cvt_pk_bf16_f32 v43, v48, v49
	global_load_dword v180, v[36:37], off offset:-1792
	global_load_dword v181, v[36:37], off offset:-1280
	global_load_dword v182, v[36:37], off offset:-768
	global_load_dword v183, v[36:37], off offset:-256
	global_load_dword v184, v[36:37], off offset:256
	global_load_dword v47, v[36:37], off offset:768
	global_load_dword v48, v[36:37], off offset:1280
	global_load_dword v49, v[36:37], off offset:1792
	v_mfma_f32_32x32x16_bf16 v[64:79], v[40:43], v[104:107], v[64:79]
	s_waitcnt vmcnt(56)
	v_cvt_pk_bf16_f32 v60, v50, v51
	v_cvt_pk_bf16_f32 v61, v52, v53
	v_cvt_pk_bf16_f32 v62, v54, v55
	v_cvt_pk_bf16_f32 v63, v56, v57
	global_load_dword v50, v[36:37], off offset:-1664
	global_load_dword v51, v[36:37], off offset:-1152
	global_load_dword v52, v[36:37], off offset:-640
	global_load_dword v53, v[36:37], off offset:-128
	global_load_dword v54, v[36:37], off offset:384
	global_load_dword v55, v[36:37], off offset:896
	global_load_dword v56, v[36:37], off offset:1408
	global_load_dword v57, v[36:37], off offset:1920
	v_mfma_f32_32x32x16_bf16 v[80:95], v[60:63], v[104:107], v[80:95]
	v_lshl_add_u64 v[36:37], v[36:37], 0, s[28:29]
	ds_read_b128 v[104:107], v131 offset:3072
	s_waitcnt vmcnt(56) lgkmcnt(1)
	v_cvt_pk_bf16_f32 v40, v132, v133
	v_cvt_pk_bf16_f32 v41, v134, v135
	v_cvt_pk_bf16_f32 v42, v136, v137
	v_cvt_pk_bf16_f32 v43, v138, v139
	global_load_dword v132, v[36:37], off offset:-2048
	global_load_dword v133, v[36:37], off offset:-1536
	global_load_dword v134, v[36:37], off offset:-1024
	global_load_dword v135, v[36:37], off offset:-512
	global_load_dword v136, v[36:37], off
	global_load_dword v137, v[36:37], off offset:512
	global_load_dword v138, v[36:37], off offset:1024
	global_load_dword v139, v[36:37], off offset:1536
	v_mfma_f32_32x32x16_bf16 v[0:15], v[40:43], v[32:35], v[0:15]
	s_waitcnt vmcnt(56)
	v_cvt_pk_bf16_f32 v60, v140, v141
	v_cvt_pk_bf16_f32 v61, v142, v143
	v_cvt_pk_bf16_f32 v62, v144, v145
	v_cvt_pk_bf16_f32 v63, v146, v147
	global_load_dword v140, v[36:37], off offset:-1920
	global_load_dword v141, v[36:37], off offset:-1408
	global_load_dword v142, v[36:37], off offset:-896
	global_load_dword v143, v[36:37], off offset:-384
	global_load_dword v144, v[36:37], off offset:128
	global_load_dword v145, v[36:37], off offset:640
	global_load_dword v146, v[36:37], off offset:1152
	global_load_dword v147, v[36:37], off offset:1664
	v_mfma_f32_32x32x16_bf16 v[16:31], v[60:63], v[32:35], v[16:31]
	s_waitcnt vmcnt(56)
	v_cvt_pk_bf16_f32 v40, v148, v149
	v_cvt_pk_bf16_f32 v41, v150, v151
	v_cvt_pk_bf16_f32 v42, v152, v153
	v_cvt_pk_bf16_f32 v43, v154, v155
	global_load_dword v148, v[36:37], off offset:-1792
	global_load_dword v149, v[36:37], off offset:-1280
	global_load_dword v150, v[36:37], off offset:-768
	global_load_dword v151, v[36:37], off offset:-256
	global_load_dword v152, v[36:37], off offset:256
	global_load_dword v153, v[36:37], off offset:768
	global_load_dword v154, v[36:37], off offset:1280
	global_load_dword v155, v[36:37], off offset:1792
	v_mfma_f32_32x32x16_bf16 v[64:79], v[40:43], v[32:35], v[64:79]
	s_waitcnt vmcnt(56)
	v_cvt_pk_bf16_f32 v60, v156, v157
	v_cvt_pk_bf16_f32 v61, v158, v159
	v_cvt_pk_bf16_f32 v62, v160, v161
	v_cvt_pk_bf16_f32 v63, v162, v163
	global_load_dword v156, v[36:37], off offset:-1664
	global_load_dword v157, v[36:37], off offset:-1152
	global_load_dword v158, v[36:37], off offset:-640
	global_load_dword v159, v[36:37], off offset:-128
	global_load_dword v160, v[36:37], off offset:384
	global_load_dword v161, v[36:37], off offset:896
	global_load_dword v162, v[36:37], off offset:1408
	global_load_dword v163, v[36:37], off offset:1920
	v_mfma_f32_32x32x16_bf16 v[80:95], v[60:63], v[32:35], v[80:95]
	v_lshl_add_u64 v[36:37], v[36:37], 0, s[28:29]
	ds_read_b128 v[32:35], v131 offset:4096
	s_waitcnt vmcnt(56) lgkmcnt(1)
; #define MFMA32(a, b, c) __builtin_amdgcn_mfma_f32_32x32x16_bf16((a), (b), (c), 0, 0, 0)
; __device__ __forceinline__ s16x8 pack8(const float (&x)[8]) { u32x4 p; p.x = pk2(x[0], x[1]); p.y = pk2(x[2], x[3]); p.z = pk2(x[4], x[5]); p.w = pk2(x[6], x[7]); return __builtin_bit_cast(s16x8, p); }
; template <bool SAMPLE>
; __device__ __forceinline__ void mout_task(Ctx& C, int l, int unit, int h, int tb, const LAS float* cwl, const LAS float* gainl, LAS float* gsbuf, LAS s16x8* qfl, const bool st) {
;     ...
;         for (int ks = 0; ks < 8; ++ks) { const s16x8 qv = qfl[ks * 64 + lane];
; #pragma unroll
;             for (int vb = 0; vb < 4; ++vb) { float x[8];
; #pragma unroll
;                 for (int e = 0; e < 8; ++e) x[e] = cp[(size_t)(16 * ks + 8 * hi + e) * 128 + 32 * vb];
;                 acc[vb] = MFMA32(pack8(x), qv, acc[vb]); } }
	v_cvt_pk_bf16_f32 v40, v164, v165
	v_cvt_pk_bf16_f32 v41, v166, v167
	v_cvt_pk_bf16_f32 v42, v168, v169
	v_cvt_pk_bf16_f32 v43, v170, v171
	global_load_dword v164, v[36:37], off offset:-2048
	global_load_dword v165, v[36:37], off offset:-1536
	global_load_dword v166, v[36:37], off offset:-1024
	global_load_dword v167, v[36:37], off offset:-512
	global_load_dword v168, v[36:37], off
	global_load_dword v169, v[36:37], off offset:512
	global_load_dword v170, v[36:37], off offset:1024
	global_load_dword v171, v[36:37], off offset:1536
	v_mfma_f32_32x32x16_bf16 v[0:15], v[40:43], v[104:107], v[0:15]
	s_waitcnt vmcnt(56)
	v_cvt_pk_bf16_f32 v60, v172, v173
	v_cvt_pk_bf16_f32 v61, v174, v175
	v_cvt_pk_bf16_f32 v62, v176, v177
	v_cvt_pk_bf16_f32 v63, v178, v179
	global_load_dword v172, v[36:37], off offset:-1920
	global_load_dword v173, v[36:37], off offset:-1408
	global_load_dword v174, v[36:37], off offset:-896
	global_load_dword v175, v[36:37], off offset:-384
	global_load_dword v176, v[36:37], off offset:128
	global_load_dword v177, v[36:37], off offset:640
	global_load_dword v178, v[36:37], off offset:1152
	global_load_dword v179, v[36:37], off offset:1664
	v_mfma_f32_32x32x16_bf16 v[16:31], v[60:63], v[104:107], v[16:31]
	s_waitcnt vmcnt(56)
	v_cvt_pk_bf16_f32 v40, v180, v181
	v_cvt_pk_bf16_f32 v41, v182, v183
	v_cvt_pk_bf16_f32 v42, v184, v47
	v_cvt_pk_bf16_f32 v43, v48, v49
	global_load_dword v180, v[36:37], off offset:-1792
	global_load_dword v181, v[36:37], off offset:-1280
	global_load_dword v182, v[36:37], off offset:-768
	global_load_dword v183, v[36:37], off offset:-256
	global_load_dword v184, v[36:37], off offset:256
	global_load_dword v47, v[36:37], off offset:768
	global_load_dword v48, v[36:37], off offset:1280
	global_load_dword v49, v[36:37], off offset:1792
	v_mfma_f32_32x32x16_bf16 v[64:79], v[40:43], v[104:107], v[64:79]
	s_waitcnt vmcnt(56)
	v_cvt_pk_bf16_f32 v60, v50, v51
	v_cvt_pk_bf16_f32 v61, v52, v53
	v_cvt_pk_bf16_f32 v62, v54, v55
	v_cvt_pk_bf16_f32 v63, v56, v57
	global_load_dword v50, v[36:37], off offset:-1664
	global_load_dword v51, v[36:37], off offset:-1152
	global_load_dword v52, v[36:37], off offset:-640
	global_load_dword v53, v[36:37], off offset:-128
	global_load_dword v54, v[36:37], off offset:384
	global_load_dword v55, v[36:37], off offset:896
	global_load_dword v56, v[36:37], off offset:1408
	global_load_dword v57, v[36:37], off offset:1920
	v_mfma_f32_32x32x16_bf16 v[80:95], v[60:63], v[104:107], v[80:95]
	v_lshl_add_u64 v[36:37], v[36:37], 0, s[28:29]
	ds_read_b128 v[104:107], v131 offset:5120
	s_waitcnt vmcnt(56) lgkmcnt(1)
	v_cvt_pk_bf16_f32 v40, v132, v133
	v_cvt_pk_bf16_f32 v41, v134, v135
	v_cvt_pk_bf16_f32 v42, v136, v137
	v_cvt_pk_bf16_f32 v43, v138, v139
	global_load_dword v132, v[36:37], off offset:-2048
	global_load_dword v133, v[36:37], off offset:-1536
	global_load_dword v134, v[36:37], off offset:-1024
	global_load_dword v135, v[36:37], off offset:-512
	global_load_dword v136, v[36:37], off
	global_load_dword v137, v[36:37], off offset:512
	global_load_dword v138, v[36:37], off offset:1024
	global_load_dword v139, v[36:37], off offset:1536
	v_mfma_f32_32x32x16_bf16 v[0:15], v[40:43], v[32:35], v[0:15]
	s_waitcnt vmcnt(56)
	v_cvt_pk_bf16_f32 v60, v140, v141
	v_cvt_pk_bf16_f32 v61, v142, v143
	v_cvt_pk_bf16_f32 v62, v144, v145
	v_cvt_pk_bf16_f32 v63, v146, v147
	global_load_dword v140, v[36:37], off offset:-1920
	global_load_dword v141, v[36:37], off offset:-1408
	global_load_dword v142, v[36:37], off offset:-896
	global_load_dword v143, v[36:37], off offset:-384
	global_load_dword v144, v[36:37], off offset:128
	global_load_dword v145, v[36:37], off offset:640
	global_load_dword v146, v[36:37], off offset:1152
	global_load_dword v147, v[36:37], off offset:1664
	v_mfma_f32_32x32x16_bf16 v[16:31], v[60:63], v[32:35], v[16:31]
	s_waitcnt vmcnt(56)
	v_cvt_pk_bf16_f32 v40, v148, v149
	v_cvt_pk_bf16_f32 v41, v150, v151
	v_cvt_pk_bf16_f32 v42, v152, v153
	v_cvt_pk_bf16_f32 v43, v154, v155
	global_load_dword v148, v[36:37], off offset:-1792
	global_load_dword v149, v[36:37], off offset:-1280
	global_load_dword v150, v[36:37], off offset:-768
	global_load_dword v151, v[36:37], off offset:-256
	global_load_dword v152, v[36:37], off offset:256
	global_load_dword v153, v[36:37], off offset:768
	global_load_dword v154, v[36:37], off offset:1280
	global_load_dword v155, v[36:37], off offset:1792
	v_mfma_f32_32x32x16_bf16 v[64:79], v[40:43], v[32:35], v[64:79]
	s_waitcnt vmcnt(56)
	v_cvt_pk_bf16_f32 v60, v156, v157
	v_cvt_pk_bf16_f32 v61, v158, v159
	v_cvt_pk_bf16_f32 v62, v160, v161
	v_cvt_pk_bf16_f32 v63, v162, v163
	global_load_dword v156, v[36:37], off offset:-1664
	global_load_dword v157, v[36:37], off offset:-1152
	global_load_dword v158, v[36:37], off offset:-640
	global_load_dword v159, v[36:37], off offset:-128
	global_load_dword v160, v[36:37], off offset:384
	global_load_dword v161, v[36:37], off offset:896
	global_load_dword v162, v[36:37], off offset:1408
	global_load_dword v163, v[36:37], off offset:1920
	v_mfma_f32_32x32x16_bf16 v[80:95], v[60:63], v[32:35], v[80:95]
	v_lshl_add_u64 v[36:37], v[36:37], 0, s[28:29]
	ds_read_b128 v[32:35], v131 offset:6144
	s_waitcnt vmcnt(56) lgkmcnt(1)
	v_cvt_pk_bf16_f32 v40, v164, v165
	v_cvt_pk_bf16_f32 v41, v166, v167
	v_cvt_pk_bf16_f32 v42, v168, v169
	v_cvt_pk_bf16_f32 v43, v170, v171
	global_load_dword v164, v[36:37], off offset:-2048
	global_load_dword v165, v[36:37], off offset:-1536
	global_load_dword v166, v[36:37], off offset:-1024
	global_load_dword v167, v[36:37], off offset:-512
	global_load_dword v168, v[36:37], off
	global_load_dword v169, v[36:37], off offset:512
	global_load_dword v170, v[36:37], off offset:1024
	global_load_dword v171, v[36:37], off offset:1536
	v_mfma_f32_32x32x16_bf16 v[0:15], v[40:43], v[104:107], v[0:15]
	s_waitcnt vmcnt(56)
; #define MFMA32(a, b, c) __builtin_amdgcn_mfma_f32_32x32x16_bf16((a), (b), (c), 0, 0, 0)
; __device__ __forceinline__ s16x8 pack8(const float (&x)[8]) { u32x4 p; p.x = pk2(x[0], x[1]); p.y = pk2(x[2], x[3]); p.z = pk2(x[4], x[5]); p.w = pk2(x[6], x[7]); return __builtin_bit_cast(s16x8, p); }
;     __device__ __forceinline__ bf16* U() const { return (bf16*)(ws + WS_U); }
;     __device__ __forceinline__ bf16* DC() const { return (bf16*)(ws + WS_XN); }
; template <bool SAMPLE>
; __device__ __forceinline__ void mout_task(Ctx& C, int l, int unit, int h, int tb, const LAS float* cwl, const LAS float* gainl, LAS float* gsbuf, LAS s16x8* qfl, const bool st) {
;     ...
;                 for (int e = 0; e < 8; ++e) x[e] = cp[(size_t)(16 * ks + 8 * hi + e) * 128 + 32 * vb];
;                 acc[vb] = MFMA32(pack8(x), qv, acc[vb]); } }
;     } else {
;         const bf16* cp = C.DC() + (size_t)slot * 16384 + (size_t)r * 128 + 8 * hi;
; #pragma unroll 1
;         for (int ks = 0; ks < 8; ++ks) { const s16x8 qv = qfl[ks * 64 + lane];
; #pragma unroll
;             for (int vb = 0; vb < 4; ++vb) acc[vb] = MFMA32(*(const s16x8*)(cp + (size_t)vb * 4096 + 16 * ks), qv, acc[vb]); }
;     }
; #pragma unroll
;     for (int vb = 0; vb < 4; ++vb)
; #pragma unroll
;         for (int i = 0; i < 16; ++i) acc[vb][i] *= winter;
;     ...
;         { s16x8 tk[8];
;           const bf16* kp = C.U() + (grow0 + sl) * UW + C_KM + h * 128 + 8 * hi;
; #pragma unroll
;           for (int ks = 0; ks < 8; ++ks) tk[ks] = *(const s16x8*)(kp + 16 * ks);
	v_cvt_pk_bf16_f32 v60, v172, v173
	v_cvt_pk_bf16_f32 v61, v174, v175
	v_cvt_pk_bf16_f32 v62, v176, v177
	v_cvt_pk_bf16_f32 v63, v178, v179
	global_load_dword v172, v[36:37], off offset:-1920
	global_load_dword v173, v[36:37], off offset:-1408
	global_load_dword v174, v[36:37], off offset:-896
	global_load_dword v175, v[36:37], off offset:-384
	global_load_dword v176, v[36:37], off offset:128
	global_load_dword v177, v[36:37], off offset:640
	global_load_dword v178, v[36:37], off offset:1152
	global_load_dword v179, v[36:37], off offset:1664
	v_mfma_f32_32x32x16_bf16 v[16:31], v[60:63], v[104:107], v[16:31]
	s_waitcnt vmcnt(56)
	v_cvt_pk_bf16_f32 v40, v180, v181
	v_cvt_pk_bf16_f32 v41, v182, v183
	v_cvt_pk_bf16_f32 v42, v184, v47
	v_cvt_pk_bf16_f32 v43, v48, v49
	global_load_dword v180, v[36:37], off offset:-1792
	global_load_dword v181, v[36:37], off offset:-1280
	global_load_dword v182, v[36:37], off offset:-768
	global_load_dword v183, v[36:37], off offset:-256
	global_load_dword v184, v[36:37], off offset:256
	global_load_dword v47, v[36:37], off offset:768
	global_load_dword v48, v[36:37], off offset:1280
	global_load_dword v49, v[36:37], off offset:1792
	v_mfma_f32_32x32x16_bf16 v[64:79], v[40:43], v[104:107], v[64:79]
	s_waitcnt vmcnt(56)
	v_cvt_pk_bf16_f32 v60, v50, v51
	v_cvt_pk_bf16_f32 v61, v52, v53
	v_cvt_pk_bf16_f32 v62, v54, v55
	v_cvt_pk_bf16_f32 v63, v56, v57
	global_load_dword v50, v[36:37], off offset:-1664
	global_load_dword v51, v[36:37], off offset:-1152
	global_load_dword v52, v[36:37], off offset:-640
	global_load_dword v53, v[36:37], off offset:-128
	global_load_dword v54, v[36:37], off offset:384
	global_load_dword v55, v[36:37], off offset:896
	global_load_dword v56, v[36:37], off offset:1408
	global_load_dword v57, v[36:37], off offset:1920
	v_mfma_f32_32x32x16_bf16 v[80:95], v[60:63], v[104:107], v[80:95]
	v_lshl_add_u64 v[36:37], v[36:37], 0, s[28:29]
	ds_read_b128 v[104:107], v131 offset:7168
	s_waitcnt vmcnt(56) lgkmcnt(1)
	v_cvt_pk_bf16_f32 v40, v132, v133
	v_cvt_pk_bf16_f32 v41, v134, v135
	v_cvt_pk_bf16_f32 v42, v136, v137
	v_cvt_pk_bf16_f32 v43, v138, v139
	s_nop 1
	v_mfma_f32_32x32x16_bf16 v[0:15], v[40:43], v[32:35], v[0:15]
	s_waitcnt vmcnt(48)
	v_cvt_pk_bf16_f32 v60, v140, v141
	v_cvt_pk_bf16_f32 v61, v142, v143
	v_cvt_pk_bf16_f32 v62, v144, v145
	v_cvt_pk_bf16_f32 v63, v146, v147
	s_nop 1
	v_mfma_f32_32x32x16_bf16 v[16:31], v[60:63], v[32:35], v[16:31]
	s_waitcnt vmcnt(40)
	v_cvt_pk_bf16_f32 v40, v148, v149
	v_cvt_pk_bf16_f32 v41, v150, v151
	v_cvt_pk_bf16_f32 v42, v152, v153
	v_cvt_pk_bf16_f32 v43, v154, v155
	s_nop 1
	v_mfma_f32_32x32x16_bf16 v[64:79], v[40:43], v[32:35], v[64:79]
	s_waitcnt vmcnt(32)
	v_cvt_pk_bf16_f32 v60, v156, v157
	v_cvt_pk_bf16_f32 v61, v158, v159
	v_cvt_pk_bf16_f32 v62, v160, v161
	v_cvt_pk_bf16_f32 v63, v162, v163
	s_nop 1
	v_mfma_f32_32x32x16_bf16 v[80:95], v[60:63], v[32:35], v[80:95]
	s_waitcnt vmcnt(24) lgkmcnt(0)
	v_cvt_pk_bf16_f32 v40, v164, v165
	v_cvt_pk_bf16_f32 v41, v166, v167
	v_cvt_pk_bf16_f32 v42, v168, v169
	v_cvt_pk_bf16_f32 v43, v170, v171
	s_nop 1
	v_mfma_f32_32x32x16_bf16 v[0:15], v[40:43], v[104:107], v[0:15]
	s_waitcnt vmcnt(16)
	v_cvt_pk_bf16_f32 v60, v172, v173
	v_cvt_pk_bf16_f32 v61, v174, v175
	v_cvt_pk_bf16_f32 v62, v176, v177
	v_cvt_pk_bf16_f32 v63, v178, v179
	s_nop 1
	v_mfma_f32_32x32x16_bf16 v[16:31], v[60:63], v[104:107], v[16:31]
	s_waitcnt vmcnt(8)
	v_cvt_pk_bf16_f32 v40, v180, v181
	v_cvt_pk_bf16_f32 v41, v182, v183
	v_cvt_pk_bf16_f32 v42, v184, v47
	v_cvt_pk_bf16_f32 v43, v48, v49
	s_nop 1
	v_mfma_f32_32x32x16_bf16 v[64:79], v[40:43], v[104:107], v[64:79]
	s_waitcnt vmcnt(0)
	v_cvt_pk_bf16_f32 v60, v50, v51
	v_cvt_pk_bf16_f32 v61, v52, v53
	v_cvt_pk_bf16_f32 v62, v54, v55
	v_cvt_pk_bf16_f32 v63, v56, v57
	s_nop 1
	v_mfma_f32_32x32x16_bf16 v[80:95], v[60:63], v[104:107], v[80:95]
	s_movk_i32 s5, 0x2000
	v_add_f32_e32 v32, v38, v97
	v_sub_f32_e32 v32, v32, v101
	v_mul_f32_e32 v32, 0x3fb8aa3b, v32
	v_exp_f32_e32 v100, v32
	v_lshl_add_u32 v103, v116, 2, s3
	s_mov_b32 s6, 0x3fb8aa3b
	v_cmp_gt_u32_e32 vcc, v192, v129
	v_pk_mul_f32 v[32:33], v[100:101], v[16:17] op_sel_hi:[0,1]
	v_pk_mul_f32 v[16:17], v[100:101], v[64:65] op_sel_hi:[0,1]
	v_or_b32_e32 v64, s4, v192
	v_mul_u32_u24_e32 v64, 0x8400, v64
	v_lshlrev_b32_e32 v64, 1, v64
	v_mov_b32_e32 v65, v193
	v_lshl_add_u64 v[64:65], s[90:91], 0, v[64:65]
	v_pk_mul_f32 v[60:61], v[100:101], v[12:13] op_sel_hi:[0,1]
	v_pk_mul_f32 v[58:59], v[100:101], v[10:11] op_sel_hi:[0,1]
	v_pk_mul_f32 v[56:57], v[100:101], v[8:9] op_sel_hi:[0,1]
	v_pk_mul_f32 v[54:55], v[100:101], v[6:7] op_sel_hi:[0,1]
	v_pk_mul_f32 v[52:53], v[100:101], v[4:5] op_sel_hi:[0,1]
	v_pk_mul_f32 v[50:51], v[100:101], v[2:3] op_sel_hi:[0,1]
	v_pk_mul_f32 v[48:49], v[100:101], v[0:1] op_sel_hi:[0,1]
	v_pk_mul_f32 v[34:35], v[100:101], v[18:19] op_sel_hi:[0,1]
	v_pk_mul_f32 v[18:19], v[100:101], v[66:67] op_sel_hi:[0,1]
	v_pk_mul_f32 v[12:13], v[100:101], v[92:93] op_sel_hi:[0,1]
	v_pk_mul_f32 v[10:11], v[100:101], v[90:91] op_sel_hi:[0,1]
	v_pk_mul_f32 v[8:9], v[100:101], v[88:89] op_sel_hi:[0,1]
	v_pk_mul_f32 v[6:7], v[100:101], v[86:87] op_sel_hi:[0,1]
	v_pk_mul_f32 v[4:5], v[100:101], v[84:85] op_sel_hi:[0,1]
	v_pk_mul_f32 v[2:3], v[100:101], v[82:83] op_sel_hi:[0,1]
	v_pk_mul_f32 v[0:1], v[100:101], v[80:81] op_sel_hi:[0,1]
	v_lshl_add_u64 v[92:93], s[40:41], 1, v[64:65]
	global_load_dwordx4 v[64:67], v[98:99], off offset:3072
	global_load_dwordx4 v[80:83], v[98:99], off offset:3104
	global_load_dwordx4 v[84:87], v[98:99], off offset:3136
	global_load_dwordx4 v[88:91], v[98:99], off offset:3168
	global_load_dwordx4 v[104:107], v[98:99], off offset:3200
; #define MFMA32(a, b, c) __builtin_amdgcn_mfma_f32_32x32x16_bf16((a), (b), (c), 0, 0, 0)
;     __device__ __forceinline__ bf16* KVt() const { return (bf16*)(ws + WS_KVT); }
; template <bool SAMPLE>
; __device__ __forceinline__ void mout_task(Ctx& C, int l, int unit, int h, int tb, const LAS float* cwl, const LAS float* gainl, LAS float* gsbuf, LAS s16x8* qfl, const bool st) {
;     ...
;           for (int ks = 0; ks < 8; ++ks) S = MFMA32(tk[ks], qfl[ks * 64 + lane], S); }
;     ...
;             const bf16* vp0 = C.KVt() + (size_t)(R_VM + h * 128 + r) * MT + grow0 + 32 * sb + 16 * s2 + 4 * hi;
; #pragma unroll
;             for (int vb = 0; vb < 4; ++vb) { const bf16* vp = vp0 + (size_t)(32 * vb) * MT;
;                 const u32x2 a = *(const u32x2*)vp, bq = *(const u32x2*)(vp + 8); u32x4 vw; vw.x = a.x; vw.y = a.y; vw.z = bq.x; vw.w = bq.y;
;                 acc[vb] = MFMA32(__builtin_bit_cast(s16x8, vw), pf, acc[vb]); } }
	global_load_dwordx4 v[108:111], v[98:99], off offset:3232
	global_load_dwordx4 v[116:119], v[98:99], off offset:3264
	global_load_dwordx4 v[120:123], v[98:99], off offset:3296
	v_pk_mul_f32 v[38:39], v[100:101], v[22:23] op_sel_hi:[0,1]
	v_pk_mul_f32 v[36:37], v[100:101], v[20:21] op_sel_hi:[0,1]
	v_pk_mul_f32 v[22:23], v[100:101], v[70:71] op_sel_hi:[0,1]
	v_pk_mul_f32 v[20:21], v[100:101], v[68:69] op_sel_hi:[0,1]
	ds_read_b128 v[68:71], v127 offset:32768
	ds_read_b128 v[130:133], v127 offset:33792
	v_pk_mul_f32 v[46:47], v[100:101], v[30:31] op_sel_hi:[0,1]
	v_pk_mul_f32 v[44:45], v[100:101], v[28:29] op_sel_hi:[0,1]
	v_pk_mul_f32 v[42:43], v[100:101], v[26:27] op_sel_hi:[0,1]
	v_pk_mul_f32 v[40:41], v[100:101], v[24:25] op_sel_hi:[0,1]
	v_pk_mul_f32 v[30:31], v[100:101], v[78:79] op_sel_hi:[0,1]
	v_pk_mul_f32 v[28:29], v[100:101], v[76:77] op_sel_hi:[0,1]
	v_pk_mul_f32 v[26:27], v[100:101], v[74:75] op_sel_hi:[0,1]
	v_pk_mul_f32 v[24:25], v[100:101], v[72:73] op_sel_hi:[0,1]
	v_pk_mul_f32 v[62:63], v[100:101], v[14:15] op_sel_hi:[0,1]
	v_pk_mul_f32 v[14:15], v[100:101], v[94:95] op_sel_hi:[0,1]
	v_sub_f32_e32 v94, v97, v101
	v_or_b32_e32 v97, 3, v129
	v_or_b32_e32 v113, 17, v129
	v_or_b32_e32 v115, 19, v129
	s_mov_b32 s5, 0x14a00000
	ds_bpermute_b32 v102, v125, v96
	s_lshl_b32 s78, s4, 1
	s_lshl_b32 s4, s4, 2
	s_add_i32 s4, s4, 0
	s_waitcnt vmcnt(7) lgkmcnt(2)
	v_mfma_f32_32x32x16_bf16 v[64:79], v[64:67], v[68:71], 0
	s_waitcnt vmcnt(6) lgkmcnt(1)
	v_mfma_f32_32x32x16_bf16 v[64:79], v[80:83], v[130:133], v[64:79]
	ds_read_b128 v[80:83], v127 offset:34816
	s_waitcnt vmcnt(5) lgkmcnt(0)
	v_mfma_f32_32x32x16_bf16 v[64:79], v[84:87], v[80:83], v[64:79]
	ds_read_b128 v[80:83], v127 offset:35840
	s_waitcnt vmcnt(4) lgkmcnt(0)
	v_mfma_f32_32x32x16_bf16 v[64:79], v[88:91], v[80:83], v[64:79]
	ds_read_b128 v[80:83], v127 offset:36864
	s_waitcnt vmcnt(3) lgkmcnt(0)
	v_mfma_f32_32x32x16_bf16 v[64:79], v[104:107], v[80:83], v[64:79]
	ds_read_b128 v[80:83], v127 offset:37888
	s_waitcnt vmcnt(2) lgkmcnt(0)
	v_mfma_f32_32x32x16_bf16 v[64:79], v[108:111], v[80:83], v[64:79]
	ds_read_b128 v[80:83], v127 offset:38912
	v_or_b32_e32 v108, 9, v129
	v_or_b32_e32 v109, 8, v129
	v_or_b32_e32 v110, 11, v129
	v_or_b32_e32 v111, 10, v129
	s_waitcnt vmcnt(1) lgkmcnt(0)
	v_mfma_f32_32x32x16_bf16 v[64:79], v[116:119], v[80:83], v[64:79]
	ds_read_b128 v[80:83], v127 offset:39936
	v_or_b32_e32 v116, 18, v129
	v_or_b32_e32 v117, 25, v129
	v_or_b32_e32 v118, 24, v129
	v_or_b32_e32 v119, 27, v129
	s_waitcnt vmcnt(0) lgkmcnt(0)
	v_mfma_f32_32x32x16_bf16 v[64:79], v[120:123], v[80:83], v[64:79]
	v_lshlrev_b32_e32 v130, 1, v129
	v_mov_b32_e32 v131, 0
	v_lshl_add_u64 v[132:133], v[92:93], 0, v[130:131]
	s_mov_b64 s[72:73], 0x14a00000
	v_lshl_add_u64 v[134:135], v[132:133], 0, s[72:73]
	s_mov_b64 s[72:73], 0x14c10000
	v_lshl_add_u64 v[136:137], v[132:133], 0, s[72:73]
	s_mov_b64 s[72:73], 0x14e20000
	v_lshl_add_u64 v[138:139], v[132:133], 0, s[72:73]
	s_mov_b64 s[72:73], 0x15030000
	v_lshl_add_u64 v[140:141], v[132:133], 0, s[72:73]
	global_load_dwordx2 v[144:145], v[134:135], off
	global_load_dwordx2 v[146:147], v[134:135], off offset:16
	global_load_dwordx2 v[148:149], v[136:137], off
	global_load_dwordx2 v[150:151], v[136:137], off offset:16
	global_load_dwordx2 v[152:153], v[138:139], off
	global_load_dwordx2 v[154:155], v[138:139], off offset:16
	global_load_dwordx2 v[156:157], v[140:141], off
	global_load_dwordx2 v[158:159], v[140:141], off offset:16
	global_load_dwordx2 v[160:161], v[134:135], off offset:32
	global_load_dwordx2 v[162:163], v[134:135], off offset:48
	global_load_dwordx2 v[164:165], v[136:137], off offset:32
	global_load_dwordx2 v[166:167], v[136:137], off offset:48
	global_load_dwordx2 v[168:169], v[138:139], off offset:32
	global_load_dwordx2 v[170:171], v[138:139], off offset:48
	global_load_dwordx2 v[172:173], v[140:141], off offset:32
	global_load_dwordx2 v[174:175], v[140:141], off offset:48
	v_sub_u32_e32 v80, v103, v114
	ds_read_b128 v[104:107], v80 offset:22528
	ds_read_b128 v[88:91], v80 offset:22560
	ds_read_b128 v[84:87], v80 offset:22592
	ds_read_b128 v[80:83], v80 offset:22624
	v_or_b32_e32 v103, 2, v129
	v_or_b32_e32 v114, 16, v129
	v_or_b32_e32 v120, 26, v129
	s_waitcnt lgkmcnt(0)
; #define LAS __attribute__((address_space(3)))
; __device__ __forceinline__ unsigned pk2(float lo, float hi) { f32x2_t v = {lo, hi}; bf16x2_t b = __builtin_convertvector(v, bf16x2_t); return __builtin_bit_cast(unsigned, b); }
; #define MFMA32(a, b, c) __builtin_amdgcn_mfma_f32_32x32x16_bf16((a), (b), (c), 0, 0, 0)
;     __device__ __forceinline__ bf16* KVt() const { return (bf16*)(ws + WS_KVT); }
; template <bool SAMPLE>
; __device__ __forceinline__ void mout_task(Ctx& C, int l, int unit, int h, int tb, const LAS float* cwl, const LAS float* gainl, LAS float* gsbuf, LAS s16x8* qfl, const bool st) {
;     ...
;         const float e0 = (bt - mt) * LOG2E;
; #pragma unroll
;         for (int i4 = 0; i4 < 4; ++i4) { const f32x4 gs = *(const LAS f32x4*)(gsbuf + 32 * sb + 8 * i4 + 4 * hi);
; #pragma unroll
;             for (int e = 0; e < 4; ++e) { const int sidx = 32 * sb + 8 * i4 + 4 * hi + e;
;                 const float wv = (sidx <= tl) ? __builtin_amdgcn_exp2f(e0 + gs[e] * LOG2E) : 0.f;
;                 S[4 * i4 + e] *= wv; den += S[4 * i4 + e]; } }
; #pragma unroll
;         for (int s2 = 0; s2 < 2; ++s2) { u32x4 w; w.x = pk2(S[8 * s2], S[8 * s2 + 1]); w.y = pk2(S[8 * s2 + 2], S[8 * s2 + 3]); w.z = pk2(S[8 * s2 + 4], S[8 * s2 + 5]); w.w = pk2(S[8 * s2 + 6], S[8 * s2 + 7]);
;             const s16x8 pf = __builtin_bit_cast(s16x8, w);
;             const bf16* vp0 = C.KVt() + (size_t)(R_VM + h * 128 + r) * MT + grow0 + 32 * sb + 16 * s2 + 4 * hi;
; #pragma unroll
;             for (int vb = 0; vb < 4; ++vb) { const bf16* vp = vp0 + (size_t)(32 * vb) * MT;
;                 const u32x2 a = *(const u32x2*)vp, bq = *(const u32x2*)(vp + 8); u32x4 vw; vw.x = a.x; vw.y = a.y; vw.z = bq.x; vw.w = bq.y;
;                 acc[vb] = MFMA32(__builtin_bit_cast(s16x8, vw), pf, acc[vb]); } }
	v_mov_b32_e32 v95, v83
	v_pk_mul_f32 v[94:95], v[94:95], s[6:7] op_sel_hi:[1,0]
	s_mov_b64 s[6:7], 0x14a00000
	v_fmamk_f32 v98, v105, 0x3fb8aa3b, v94
	v_fmamk_f32 v83, v104, 0x3fb8aa3b, v94
	v_exp_f32_e32 v98, v98
	v_exp_f32_e32 v83, v83
	v_cndmask_b32_e32 v99, 0, v98, vcc
	v_cmp_le_u32_e32 vcc, v129, v192
	s_nop 1
	v_cndmask_b32_e32 v98, 0, v83, vcc
	v_pk_mul_f32 v[64:65], v[64:65], v[98:99]
	v_fmamk_f32 v99, v107, 0x3fb8aa3b, v94
	v_fmamk_f32 v98, v106, 0x3fb8aa3b, v94
	v_exp_f32_e32 v99, v99
	v_exp_f32_e32 v98, v98
	v_cmp_le_u32_e32 vcc, v97, v192
	v_add_f32_e32 v83, 0, v64
	v_add_f32_e32 v83, v65, v83
	v_cndmask_b32_e32 v99, 0, v99, vcc
	v_cmp_le_u32_e32 vcc, v103, v192
	s_nop 1
	v_cndmask_b32_e32 v98, 0, v98, vcc
	v_pk_mul_f32 v[98:99], v[66:67], v[98:99]
	v_fmamk_f32 v67, v89, 0x3fb8aa3b, v94
	v_add_f32_e32 v66, v98, v83
	v_add_f32_e32 v83, v99, v66
	v_fmamk_f32 v66, v88, 0x3fb8aa3b, v94
	v_exp_f32_e32 v67, v67
	v_exp_f32_e32 v66, v66
	v_cmp_le_u32_e32 vcc, v108, v192
	s_nop 1
	v_cndmask_b32_e32 v67, 0, v67, vcc
	v_cmp_le_u32_e32 vcc, v109, v192
	s_nop 1
	v_cndmask_b32_e32 v66, 0, v66, vcc
	v_pk_mul_f32 v[88:89], v[68:69], v[66:67]
	v_fmamk_f32 v67, v91, 0x3fb8aa3b, v94
	v_add_f32_e32 v66, v88, v83
	v_add_f32_e32 v68, v89, v66
	v_fmamk_f32 v66, v90, 0x3fb8aa3b, v94
	v_exp_f32_e32 v67, v67
	v_exp_f32_e32 v66, v66
	v_cmp_le_u32_e32 vcc, v110, v192
	s_nop 1
	v_cndmask_b32_e32 v67, 0, v67, vcc
	v_cmp_le_u32_e32 vcc, v111, v192
	s_nop 1
	v_cndmask_b32_e32 v66, 0, v66, vcc
	v_pk_mul_f32 v[90:91], v[70:71], v[66:67]
	v_fmamk_f32 v67, v85, 0x3fb8aa3b, v94
	v_add_f32_e32 v66, v90, v68
	v_add_f32_e32 v70, v91, v66
	v_fmamk_f32 v66, v84, 0x3fb8aa3b, v94
	v_exp_f32_e32 v67, v67
	v_exp_f32_e32 v66, v66
	v_cmp_le_u32_e32 vcc, v113, v192
	v_add_f32_e32 v71, v94, v95
	v_exp_f32_e32 v71, v71
	v_cndmask_b32_e32 v67, 0, v67, vcc
	v_cmp_le_u32_e32 vcc, v114, v192
	s_nop 1
	v_cndmask_b32_e32 v66, 0, v66, vcc
	v_pk_mul_f32 v[68:69], v[72:73], v[66:67]
	v_fmamk_f32 v67, v87, 0x3fb8aa3b, v94
	v_add_f32_e32 v66, v68, v70
	v_add_f32_e32 v70, v69, v66
	v_fmamk_f32 v66, v86, 0x3fb8aa3b, v94
	v_exp_f32_e32 v67, v67
	v_exp_f32_e32 v66, v66
	v_cmp_le_u32_e32 vcc, v115, v192
	s_nop 1
	v_cndmask_b32_e32 v67, 0, v67, vcc
	v_cmp_le_u32_e32 vcc, v116, v192
	s_nop 1
	v_cndmask_b32_e32 v66, 0, v66, vcc
	v_pk_mul_f32 v[72:73], v[74:75], v[66:67]
	v_fmamk_f32 v67, v81, 0x3fb8aa3b, v94
	v_add_f32_e32 v66, v72, v70
	v_add_f32_e32 v97, v73, v66
	v_fmamk_f32 v66, v80, 0x3fb8aa3b, v94
	v_exp_f32_e32 v67, v67
	v_exp_f32_e32 v66, v66
	v_cmp_le_u32_e32 vcc, v117, v192
	v_fmamk_f32 v70, v82, 0x3fb8aa3b, v94
	v_exp_f32_e32 v70, v70
	v_cndmask_b32_e32 v67, 0, v67, vcc
	v_cmp_le_u32_e32 vcc, v118, v192
	v_cvt_pk_bf16_f32 v74, v64, v65
	v_cvt_pk_bf16_f32 v75, v98, v99
	v_cndmask_b32_e32 v66, 0, v66, vcc
	v_cmp_le_u32_e32 vcc, v119, v192
	v_pk_mul_f32 v[66:67], v[76:77], v[66:67]
	v_cvt_pk_bf16_f32 v76, v88, v89
	v_cndmask_b32_e32 v71, 0, v71, vcc
	v_cmp_le_u32_e32 vcc, v120, v192
	v_lshlrev_b32_e32 v192, 1, v129
	v_lshl_add_u64 v[82:83], v[92:93], 0, v[192:193]
	v_cndmask_b32_e32 v70, 0, v70, vcc
	v_add_co_u32_e32 v64, vcc, s5, v82
	v_pk_mul_f32 v[70:71], v[78:79], v[70:71]
	s_nop 0
	v_addc_co_u32_e32 v65, vcc, 0, v83, vcc
	v_lshl_add_u64 v[84:85], v[82:83], 0, s[6:7]
	s_mov_b32 s5, 0x14c10000
	v_add_co_u32_e32 v64, vcc, s5, v82
	v_cvt_pk_bf16_f32 v77, v90, v91
	s_nop 0
	v_addc_co_u32_e32 v65, vcc, 0, v83, vcc
	s_waitcnt vmcnt(14)
	v_mfma_f32_32x32x16_bf16 v[48:63], v[144:147], v[74:77], v[48:63]
	s_mov_b32 s5, 0x14e20000
	v_add_co_u32_e32 v86, vcc, s5, v82
	s_mov_b32 s5, 0x15030000
	s_nop 0
	v_addc_co_u32_e32 v87, vcc, 0, v83, vcc
	s_waitcnt vmcnt(12)
	v_mfma_f32_32x32x16_bf16 v[32:47], v[148:151], v[74:77], v[32:47]
	v_add_co_u32_e32 v82, vcc, s5, v82
	s_nop 1
	v_addc_co_u32_e32 v83, vcc, 0, v83, vcc
	s_waitcnt vmcnt(10)
	v_mfma_f32_32x32x16_bf16 v[16:31], v[152:155], v[74:77], v[16:31]
	s_waitcnt vmcnt(8)
	v_mfma_f32_32x32x16_bf16 v[0:15], v[156:159], v[74:77], v[0:15]
	v_cvt_pk_bf16_f32 v74, v68, v69
	v_cvt_pk_bf16_f32 v75, v72, v73
	v_cvt_pk_bf16_f32 v76, v66, v67
	v_cvt_pk_bf16_f32 v77, v70, v71
	s_waitcnt vmcnt(6)
	s_nop 0
	v_mfma_f32_32x32x16_bf16 v[48:63], v[160:163], v[74:77], v[48:63]
	v_add_f32_e32 v64, v66, v97
	v_add_f32_e32 v64, v67, v64
	v_add_f32_e32 v64, v70, v64
	v_add_f32_e32 v97, v71, v64
	ds_bpermute_b32 v103, v125, v97
	s_waitcnt lgkmcnt(0)
	v_pk_add_f32 v[64:65], v[96:97], v[102:103]
	s_waitcnt vmcnt(4)
	v_mfma_f32_32x32x16_bf16 v[32:47], v[164:167], v[74:77], v[32:47]
	v_fmac_f32_e32 v65, v100, v64
	v_mul_f32_e32 v64, 0xbfb8aa3b, v101
	v_exp_f32_e32 v64, v64
	s_nop 0
	v_max_f32_e64 v64, |v65|, v64
	s_waitcnt vmcnt(2)
	v_mfma_f32_32x32x16_bf16 v[16:31], v[168:171], v[74:77], v[16:31]
	s_waitcnt vmcnt(0)
; #define LAS __attribute__((address_space(3)))
; __device__ __forceinline__ float fexp(float x) { return __builtin_amdgcn_exp2f(x * LOG2E); }
; #define MFMA32(a, b, c) __builtin_amdgcn_mfma_f32_32x32x16_bf16((a), (b), (c), 0, 0, 0)
;     __device__ __forceinline__ bf16* U() const { return (bf16*)(ws + WS_U); }
; template <bool SAMPLE>
; __device__ __forceinline__ void mout_task(Ctx& C, int l, int unit, int h, int tb, const LAS float* cwl, const LAS float* gainl, LAS float* gsbuf, LAS s16x8* qfl, const bool st) {
;     ...
;                 acc[vb] = MFMA32(__builtin_bit_cast(s16x8, vw), pf, acc[vb]); } }
;     }
;     den += __shfl_xor(den, 32);
;     den += winter * qn;
;     const float inv = __builtin_amdgcn_rcpf(fmaxf(fabsf(den), fexp(-mt)));
;     float ss = 0.f;
; #pragma unroll
;     for (int vb = 0; vb < 4; ++vb)
; #pragma unroll
;         for (int i = 0; i < 16; ++i) { acc[vb][i] *= inv; ss += acc[vb][i] * acc[vb][i]; }
;     ss += __shfl_xor(ss, 32);
;     const float rn = rsqrtf(ss * (1.f / 128.f) + EPS);
;     int lane2 = lane; asm volatile("" : "+v"(lane2));
;     const int hi2 = lane2 >> 5;
;     bf16* orow = C.U() + (grow0 + 32 * tb + (lane2 & 31)) * UW + C_OM + h * 128;
; #pragma unroll
;     for (int vb = 0; vb < 4; ++vb)
; #pragma unroll
;         for (int i4 = 0; i4 < 4; ++i4) { const int v0 = 32 * vb + 8 * i4 + 4 * hi2;
;             const u32x2 ow = *(const u32x2*)(orow + v0); const f32x4 gn = *(const LAS f32x4*)(gainl + h * 128 + v0);
	v_mfma_f32_32x32x16_bf16 v[0:15], v[172:175], v[74:77], v[0:15]
	v_rcp_f32_e32 v80, v64
	s_nop 10
	v_pk_mul_f32 v[72:73], v[10:11], v[80:81] op_sel_hi:[1,0]
	v_pk_mul_f32 v[68:69], v[12:13], v[80:81] op_sel_hi:[1,0]
	v_and_or_b32 v12, v112, 31, s40
	v_mov_b64_e32 v[10:11], s[90:91]
	v_mad_u64_u32 v[10:11], s[6:7], v12, s61, v[10:11]
	v_ashrrev_i32_e32 v12, 3, v112
	v_mad_i32_i24 v11, s41, v221, v11
	v_and_b32_e32 v12, -4, v12
	v_lshl_add_u64 v[10:11], v[10:11], 0, s[78:79]
	v_ashrrev_i32_e32 v13, 31, v12
	v_lshl_add_u64 v[10:11], v[12:13], 1, v[10:11]
	s_mov_b64 s[6:7], 0x1000
	v_add_co_u32_e32 v82, vcc, s60, v10
	v_pk_mul_f32 v[14:15], v[14:15], v[80:81] op_sel_hi:[1,0]
	v_lshl_add_u64 v[70:71], v[10:11], 0, s[6:7]
	v_addc_co_u32_e32 v83, vcc, 0, v11, vcc
	v_lshl_add_u32 v81, v12, 2, s4
	global_load_dwordx2 v[86:87], v[82:83], off
	ds_read_b128 v[64:67], v81 offset:20480
	ds_read_b128 v[10:13], v81 offset:20512
	v_pk_mul_f32 v[90:91], v[48:49], v[80:81] op_sel_hi:[1,0]
	global_load_dwordx2 v[48:49], v[70:71], off offset:16
	global_load_dwordx2 v[116:117], v[70:71], off offset:48
	v_pk_mul_f32 v[102:103], v[52:53], v[80:81] op_sel_hi:[1,0]
	global_load_dwordx2 v[52:53], v[70:71], off offset:32
	global_load_dwordx2 v[168:169], v[70:71], off offset:64
	global_load_dwordx2 v[170:171], v[70:71], off offset:80
	global_load_dwordx2 v[172:173], v[70:71], off offset:96
	global_load_dwordx2 v[174:175], v[70:71], off offset:112
	global_load_dwordx2 v[176:177], v[70:71], off offset:128
	global_load_dwordx2 v[180:181], v[70:71], off offset:144
	global_load_dwordx2 v[182:183], v[70:71], off offset:160
	global_load_dwordx2 v[186:187], v[70:71], off offset:176
	global_load_dwordx2 v[194:195], v[70:71], off offset:192
	global_load_dwordx2 v[196:197], v[70:71], off offset:208
	global_load_dwordx2 v[198:199], v[70:71], off offset:224
	global_load_dwordx2 v[214:215], v[70:71], off offset:240
	v_pk_mul_f32 v[88:89], v[50:51], v[80:81] op_sel_hi:[1,0]
	v_pk_mul_f32 v[94:95], v[90:91], v[90:91]
	v_pk_mul_f32 v[92:93], v[88:89], v[88:89]
	v_pk_mul_f32 v[100:101], v[54:55], v[80:81] op_sel_hi:[1,0]
	v_pk_mul_f32 v[58:59], v[58:59], v[80:81] op_sel_hi:[1,0]
	v_pk_mul_f32 v[56:57], v[56:57], v[80:81] op_sel_hi:[1,0]
	v_pk_mul_f32 v[126:127], v[62:63], v[80:81] op_sel_hi:[1,0]
	v_pk_mul_f32 v[130:131], v[60:61], v[80:81] op_sel_hi:[1,0]
	v_pk_mul_f32 v[134:135], v[34:35], v[80:81] op_sel_hi:[1,0]
	v_pk_mul_f32 v[138:139], v[32:33], v[80:81] op_sel_hi:[1,0]
	v_pk_mul_f32 v[60:61], v[42:43], v[80:81] op_sel_hi:[1,0]
	v_pk_mul_f32 v[62:63], v[40:41], v[80:81] op_sel_hi:[1,0]
	v_pk_mul_f32 v[46:47], v[46:47], v[80:81] op_sel_hi:[1,0]
	v_pk_mul_f32 v[44:45], v[44:45], v[80:81] op_sel_hi:[1,0]
	v_pk_mul_f32 v[40:41], v[18:19], v[80:81] op_sel_hi:[1,0]
	v_pk_mul_f32 v[42:43], v[16:17], v[80:81] op_sel_hi:[1,0]
	v_pk_mul_f32 v[32:33], v[26:27], v[80:81] op_sel_hi:[1,0]
	v_pk_mul_f32 v[34:35], v[24:25], v[80:81] op_sel_hi:[1,0]
	v_pk_mul_f32 v[24:25], v[30:31], v[80:81] op_sel_hi:[1,0]
	v_pk_mul_f32 v[26:27], v[28:29], v[80:81] op_sel_hi:[1,0]
	v_pk_mul_f32 v[16:17], v[6:7], v[80:81] op_sel_hi:[1,0]
	v_pk_mul_f32 v[18:19], v[4:5], v[80:81] op_sel_hi:[1,0]
	v_pk_mul_f32 v[6:7], v[8:9], v[80:81] op_sel_hi:[1,0]
	v_pk_mul_f32 v[106:107], v[102:103], v[102:103]
	v_pk_mul_f32 v[104:105], v[100:101], v[100:101]
	v_pk_mul_f32 v[114:115], v[56:57], v[56:57]
	v_pk_mul_f32 v[112:113], v[58:59], v[58:59]
	v_pk_mul_f32 v[132:133], v[130:131], v[130:131]
	v_pk_mul_f32 v[128:129], v[126:127], v[126:127]
	v_pk_mul_f32 v[140:141], v[138:139], v[138:139]
	v_pk_mul_f32 v[136:137], v[134:135], v[134:135]
	v_pk_mul_f32 v[148:149], v[62:63], v[62:63]
	v_pk_mul_f32 v[146:147], v[60:61], v[60:61]
	v_pk_mul_f32 v[152:153], v[44:45], v[44:45]
	v_pk_mul_f32 v[150:151], v[46:47], v[46:47]
	v_pk_mul_f32 v[156:157], v[42:43], v[42:43]
	v_pk_mul_f32 v[154:155], v[40:41], v[40:41]
	v_pk_mul_f32 v[164:165], v[34:35], v[34:35]
	v_pk_mul_f32 v[162:163], v[32:33], v[32:33]
	v_pk_mul_f32 v[28:29], v[26:27], v[26:27]
	v_pk_mul_f32 v[30:31], v[24:25], v[24:25]
	v_pk_mul_f32 v[4:5], v[18:19], v[18:19]
	v_pk_mul_f32 v[166:167], v[16:17], v[16:17]
	v_pk_mul_f32 v[8:9], v[6:7], v[6:7]
	v_pk_mul_f32 v[74:75], v[72:73], v[72:73]
	v_pk_mul_f32 v[76:77], v[68:69], v[68:69]
	v_pk_mul_f32 v[78:79], v[14:15], v[14:15]
	s_waitcnt vmcnt(15)
	v_lshlrev_b32_e32 v84, 16, v86
	v_and_b32_e32 v85, 0xffff0000, v86
	v_lshlrev_b32_e32 v86, 16, v87
	s_waitcnt vmcnt(14)
	v_lshlrev_b32_e32 v50, 16, v48
	s_waitcnt vmcnt(13)
; #define LAS __attribute__((address_space(3)))
; __device__ __forceinline__ unsigned pk2(float lo, float hi) { f32x2_t v = {lo, hi}; bf16x2_t b = __builtin_convertvector(v, bf16x2_t); return __builtin_bit_cast(unsigned, b); }
; __device__ __forceinline__ float bflo(unsigned w) { return __uint_as_float(w << 16); }
; __device__ __forceinline__ float bfhi(unsigned w) { return __uint_as_float(w & 0xffff0000u); }
; __device__ __forceinline__ float fexp(float x) { return __builtin_amdgcn_exp2f(x * LOG2E); }
; __device__ __forceinline__ float sigmoidf_(float x) { return __builtin_amdgcn_rcpf(1.f + fexp(-x)); }
;     __device__ __forceinline__ bf16* U() const { return (bf16*)(ws + WS_U); }
; template <bool SAMPLE>
; __device__ __forceinline__ void mout_task(Ctx& C, int l, int unit, int h, int tb, const LAS float* cwl, const LAS float* gainl, LAS float* gsbuf, LAS s16x8* qfl, const bool st) {
;     ...
;     const float inv = __builtin_amdgcn_rcpf(fmaxf(fabsf(den), fexp(-mt)));
;     float ss = 0.f;
; #pragma unroll
;     for (int vb = 0; vb < 4; ++vb)
; #pragma unroll
;         for (int i = 0; i < 16; ++i) { acc[vb][i] *= inv; ss += acc[vb][i] * acc[vb][i]; }
;     ss += __shfl_xor(ss, 32);
;     const float rn = rsqrtf(ss * (1.f / 128.f) + EPS);
;     int lane2 = lane; asm volatile("" : "+v"(lane2));
;     const int hi2 = lane2 >> 5;
;     bf16* orow = C.U() + (grow0 + 32 * tb + (lane2 & 31)) * UW + C_OM + h * 128;
; #pragma unroll
;     for (int vb = 0; vb < 4; ++vb)
; #pragma unroll
;         for (int i4 = 0; i4 < 4; ++i4) { const int v0 = 32 * vb + 8 * i4 + 4 * hi2;
;             const u32x2 ow = *(const u32x2*)(orow + v0); const f32x4 gn = *(const LAS f32x4*)(gainl + h * 128 + v0);
;             const float y0 = acc[vb][4 * i4] * rn * gn[0] * sigmoidf_(bflo(ow.x)), y1 = acc[vb][4 * i4 + 1] * rn * gn[1] * sigmoidf_(bfhi(ow.x));
;             const float y2 = acc[vb][4 * i4 + 2] * rn * gn[2] * sigmoidf_(bflo(ow.y)), y3 = acc[vb][4 * i4 + 3] * rn * gn[3] * sigmoidf_(bfhi(ow.y));
;             u32x2 w; w.x = pk2(y0, y1); w.y = pk2(y2, y3); if (st) *(u32x2*)(orow + v0) = w; if (i4 == 3) asm volatile("" ::: "memory"); }
	v_lshlrev_b32_e32 v118, 16, v116
	v_and_b32_e32 v116, 0xffff0000, v116
	v_mul_f32_e32 v116, 0xbfb8aa3b, v116
	v_exp_f32_e32 v116, v116
	v_mul_f32_e32 v118, 0xbfb8aa3b, v118
	v_exp_f32_e32 v118, v118
	v_and_b32_e32 v48, 0xffff0000, v48
	v_add_f32_e32 v116, 1.0, v116
	v_rcp_f32_e32 v121, v116
	v_lshlrev_b32_e32 v116, 16, v117
	v_mul_f32_e32 v116, 0xbfb8aa3b, v116
	v_exp_f32_e32 v116, v116
	v_add_f32_e32 v118, 1.0, v118
	v_rcp_f32_e32 v120, v118
	v_pk_mul_f32 v[118:119], v[36:37], v[80:81] op_sel_hi:[1,0]
	v_add_f32_e32 v116, 1.0, v116
	v_rcp_f32_e32 v122, v116
	v_and_b32_e32 v116, 0xffff0000, v117
	v_mul_f32_e32 v116, 0xbfb8aa3b, v116
	v_exp_f32_e32 v116, v116
	v_pk_mul_f32 v[36:37], v[22:23], v[80:81] op_sel_hi:[1,0]
	v_pk_mul_f32 v[22:23], v[0:1], v[80:81] op_sel_hi:[1,0]
	v_pk_mul_f32 v[144:145], v[118:119], v[118:119]
	v_add_f32_e32 v116, 1.0, v116
	v_rcp_f32_e32 v123, v116
	v_pk_mul_f32 v[116:117], v[38:39], v[80:81] op_sel_hi:[1,0]
	v_pk_mul_f32 v[38:39], v[20:21], v[80:81] op_sel_hi:[1,0]
	v_pk_mul_f32 v[20:21], v[2:3], v[80:81] op_sel_hi:[1,0]
	v_add_f32_e32 v80, v94, v95
	v_add_f32_e32 v80, v92, v80
	v_add_f32_e32 v80, v93, v80
	v_add_f32_e32 v80, v106, v80
	v_add_f32_e32 v80, v107, v80
	v_add_f32_e32 v80, v104, v80
	v_add_f32_e32 v80, v105, v80
	v_add_f32_e32 v80, v114, v80
	v_add_f32_e32 v80, v115, v80
	v_add_f32_e32 v80, v112, v80
	v_add_f32_e32 v80, v113, v80
	v_add_f32_e32 v80, v132, v80
	v_add_f32_e32 v80, v133, v80
	v_add_f32_e32 v80, v128, v80
	v_add_f32_e32 v80, v129, v80
	v_add_f32_e32 v80, v140, v80
	v_add_f32_e32 v80, v141, v80
	v_add_f32_e32 v80, v136, v80
	v_add_f32_e32 v80, v137, v80
	v_add_f32_e32 v80, v144, v80
	v_pk_mul_f32 v[142:143], v[116:117], v[116:117]
	v_add_f32_e32 v80, v145, v80
	v_add_f32_e32 v80, v142, v80
	v_add_f32_e32 v80, v143, v80
	v_add_f32_e32 v80, v148, v80
	v_add_f32_e32 v80, v149, v80
	v_add_f32_e32 v80, v146, v80
	v_add_f32_e32 v80, v147, v80
	v_add_f32_e32 v80, v152, v80
	v_add_f32_e32 v80, v153, v80
	v_add_f32_e32 v80, v150, v80
	v_add_f32_e32 v80, v151, v80
	v_add_f32_e32 v80, v156, v80
	v_add_f32_e32 v80, v157, v80
	v_add_f32_e32 v80, v154, v80
	v_pk_mul_f32 v[160:161], v[38:39], v[38:39]
	v_add_f32_e32 v80, v155, v80
	v_add_f32_e32 v80, v160, v80
	v_pk_mul_f32 v[158:159], v[36:37], v[36:37]
	v_add_f32_e32 v80, v161, v80
	v_add_f32_e32 v80, v158, v80
	v_add_f32_e32 v80, v159, v80
	v_add_f32_e32 v80, v164, v80
	v_add_f32_e32 v80, v165, v80
	v_add_f32_e32 v80, v162, v80
	v_add_f32_e32 v80, v163, v80
	v_add_f32_e32 v28, v28, v80
	v_add_f32_e32 v28, v29, v28
	v_add_f32_e32 v28, v30, v28
	v_pk_mul_f32 v[0:1], v[22:23], v[22:23]
	v_add_f32_e32 v28, v31, v28
	v_add_f32_e32 v0, v0, v28
	v_pk_mul_f32 v[2:3], v[20:21], v[20:21]
	v_add_f32_e32 v0, v1, v0
	v_add_f32_e32 v0, v2, v0
	v_add_f32_e32 v0, v3, v0
	v_add_f32_e32 v0, v4, v0
	v_add_f32_e32 v0, v5, v0
	v_add_f32_e32 v0, v166, v0
	v_add_f32_e32 v0, v167, v0
	v_add_f32_e32 v0, v8, v0
	v_add_f32_e32 v0, v9, v0
	v_add_f32_e32 v0, v74, v0
	v_add_f32_e32 v0, v75, v0
	v_add_f32_e32 v0, v76, v0
	v_mul_f32_e32 v48, 0xbfb8aa3b, v48
	v_add_f32_e32 v0, v77, v0
	v_exp_f32_e32 v48, v48
	v_add_f32_e32 v0, v78, v0
	v_add_f32_e32 v0, v79, v0
	s_waitcnt vmcnt(12)
	v_lshlrev_b32_e32 v54, 16, v52
	v_and_b32_e32 v52, 0xffff0000, v52
	ds_bpermute_b32 v1, v125, v0
	v_mul_f32_e32 v52, 0xbfb8aa3b, v52
	v_add_f32_e32 v48, 1.0, v48
	v_exp_f32_e32 v52, v52
	v_rcp_f32_e32 v97, v48
	v_lshlrev_b32_e32 v48, 16, v49
	v_mul_f32_e32 v48, 0xbfb8aa3b, v48
	v_exp_f32_e32 v48, v48
	s_waitcnt lgkmcnt(0)
	v_add_f32_e32 v0, v0, v1
	v_mov_b32_e32 v2, 0x358637bd
	v_and_b32_e32 v87, 0xffff0000, v87
	v_add_f32_e32 v52, 1.0, v52
	v_fmamk_f32 v0, v0, 0x3c000000, v2
	v_mul_f32_e32 v84, 0xbfb8aa3b, v84
	v_mul_f32_e32 v85, 0xbfb8aa3b, v85
	v_mul_f32_e32 v86, 0xbfb8aa3b, v86
	v_mul_f32_e32 v87, 0xbfb8aa3b, v87
	v_rcp_f32_e32 v109, v52
	v_lshlrev_b32_e32 v52, 16, v53
	v_cmp_gt_f32_e32 vcc, s65, v0
	v_mul_f32_e32 v1, 0x4b800000, v0
	v_exp_f32_e32 v84, v84
	v_exp_f32_e32 v85, v85
	v_exp_f32_e32 v86, v86
	v_exp_f32_e32 v87, v87
	v_mul_f32_e32 v52, 0xbfb8aa3b, v52
	v_cndmask_b32_e32 v0, v0, v1, vcc
	v_add_f32_e32 v48, 1.0, v48
	v_exp_f32_e32 v52, v52
	v_rsq_f32_e32 v0, v0
	v_rcp_f32_e32 v98, v48
	v_and_b32_e32 v48, 0xffff0000, v49
	v_mul_f32_e32 v50, 0xbfb8aa3b, v50
	v_mul_f32_e32 v48, 0xbfb8aa3b, v48
	v_add_f32_e32 v84, 1.0, v84
	v_add_f32_e32 v85, 1.0, v85
	v_add_f32_e32 v86, 1.0, v86
	v_add_f32_e32 v87, 1.0, v87
	v_exp_f32_e32 v50, v50
	v_exp_f32_e32 v48, v48
	v_rcp_f32_e32 v84, v84
	v_rcp_f32_e32 v85, v85
	v_rcp_f32_e32 v86, v86
	v_rcp_f32_e32 v87, v87
	v_add_f32_e32 v52, 1.0, v52
	v_mul_f32_e32 v1, 0x45800000, v0
	v_rcp_f32_e32 v110, v52
	v_and_b32_e32 v52, 0xffff0000, v53
	v_cndmask_b32_e32 v4, v0, v1, vcc
	v_mul_f32_e32 v54, 0xbfb8aa3b, v54
	v_mul_f32_e32 v52, 0xbfb8aa3b, v52
	v_pk_mul_f32 v[0:1], v[90:91], v[4:5] op_sel_hi:[1,0]
	v_pk_mul_f32 v[2:3], v[88:89], v[4:5] op_sel_hi:[1,0]
	v_add_f32_e32 v50, 1.0, v50
	v_add_f32_e32 v48, 1.0, v48
	v_exp_f32_e32 v54, v54
	v_exp_f32_e32 v52, v52
	v_pk_mul_f32 v[0:1], v[64:65], v[0:1]
	v_pk_mul_f32 v[2:3], v[66:67], v[2:3]
	v_rcp_f32_e32 v96, v50
	v_rcp_f32_e32 v99, v48
	v_pk_mul_f32 v[0:1], v[84:85], v[0:1]
	v_pk_mul_f32 v[2:3], v[86:87], v[2:3]
	v_cvt_pk_bf16_f32 v0, v0, v1
	v_cvt_pk_bf16_f32 v1, v2, v3
	ds_read_b128 v[48:51], v81 offset:20544
	global_store_dwordx2 v[82:83], v[0:1], off
	v_pk_mul_f32 v[0:1], v[102:103], v[4:5] op_sel_hi:[1,0]
	v_pk_mul_f32 v[2:3], v[100:101], v[4:5] op_sel_hi:[1,0]
	v_add_f32_e32 v54, 1.0, v54
	v_add_f32_e32 v52, 1.0, v52
	v_pk_mul_f32 v[0:1], v[10:11], v[0:1]
	v_pk_mul_f32 v[2:3], v[12:13], v[2:3]
	v_rcp_f32_e32 v108, v54
	v_rcp_f32_e32 v111, v52
	v_pk_mul_f32 v[0:1], v[96:97], v[0:1]
	v_pk_mul_f32 v[2:3], v[98:99], v[2:3]
	v_cvt_pk_bf16_f32 v0, v0, v1
	v_cvt_pk_bf16_f32 v1, v2, v3
	ds_read_b128 v[52:55], v81 offset:20576
	global_store_dwordx2 v[70:71], v[0:1], off offset:16
	v_pk_mul_f32 v[0:1], v[56:57], v[4:5] op_sel_hi:[1,0]
	v_pk_mul_f32 v[2:3], v[58:59], v[4:5] op_sel_hi:[1,0]
	s_waitcnt lgkmcnt(1)
; #define LAS __attribute__((address_space(3)))
; __device__ __forceinline__ unsigned pk2(float lo, float hi) { f32x2_t v = {lo, hi}; bf16x2_t b = __builtin_convertvector(v, bf16x2_t); return __builtin_bit_cast(unsigned, b); }
; __device__ __forceinline__ float bflo(unsigned w) { return __uint_as_float(w << 16); }
; __device__ __forceinline__ float bfhi(unsigned w) { return __uint_as_float(w & 0xffff0000u); }
; __device__ __forceinline__ float sigmoidf_(float x) { return __builtin_amdgcn_rcpf(1.f + fexp(-x)); }
; template <bool SAMPLE>
; __device__ __forceinline__ void mout_task(Ctx& C, int l, int unit, int h, int tb, const LAS float* cwl, const LAS float* gainl, LAS float* gsbuf, LAS s16x8* qfl, const bool st) {
;     ...
; #pragma unroll
;     for (int vb = 0; vb < 4; ++vb)
; #pragma unroll
;         for (int i4 = 0; i4 < 4; ++i4) { const int v0 = 32 * vb + 8 * i4 + 4 * hi2;
;             const u32x2 ow = *(const u32x2*)(orow + v0); const f32x4 gn = *(const LAS f32x4*)(gainl + h * 128 + v0);
;             const float y0 = acc[vb][4 * i4] * rn * gn[0] * sigmoidf_(bflo(ow.x)), y1 = acc[vb][4 * i4 + 1] * rn * gn[1] * sigmoidf_(bfhi(ow.x));
;             const float y2 = acc[vb][4 * i4 + 2] * rn * gn[2] * sigmoidf_(bflo(ow.y)), y3 = acc[vb][4 * i4 + 3] * rn * gn[3] * sigmoidf_(bfhi(ow.y));
;             u32x2 w; w.x = pk2(y0, y1); w.y = pk2(y2, y3); if (st) *(u32x2*)(orow + v0) = w; if (i4 == 3) asm volatile("" ::: "memory"); }
	v_pk_mul_f32 v[0:1], v[48:49], v[0:1]
	v_pk_mul_f32 v[2:3], v[50:51], v[2:3]
	v_pk_mul_f32 v[0:1], v[108:109], v[0:1]
	v_pk_mul_f32 v[2:3], v[110:111], v[2:3]
	v_cvt_pk_bf16_f32 v0, v0, v1
	v_cvt_pk_bf16_f32 v1, v2, v3
	global_store_dwordx2 v[70:71], v[0:1], off offset:32
	v_pk_mul_f32 v[0:1], v[130:131], v[4:5] op_sel_hi:[1,0]
	v_pk_mul_f32 v[2:3], v[126:127], v[4:5] op_sel_hi:[1,0]
	s_waitcnt lgkmcnt(0)
	v_pk_mul_f32 v[0:1], v[52:53], v[0:1]
	v_pk_mul_f32 v[2:3], v[54:55], v[2:3]
	v_pk_mul_f32 v[0:1], v[120:121], v[0:1]
	v_pk_mul_f32 v[2:3], v[122:123], v[2:3]
	v_cvt_pk_bf16_f32 v0, v0, v1
	v_cvt_pk_bf16_f32 v1, v2, v3
	global_store_dwordx2 v[70:71], v[0:1], off offset:48
	s_waitcnt vmcnt(4)
	v_mov_b32_e32 v12, v168
	v_mov_b32_e32 v13, v169
	ds_read_b128 v[0:3], v81 offset:20608
	ds_read_b128 v[8:11], v81 offset:20640
	v_lshlrev_b32_e32 v5, 16, v12
	v_mul_f32_e32 v5, 0xbfb8aa3b, v5
	v_exp_f32_e32 v5, v5
	s_nop 0
	v_add_f32_e32 v5, 1.0, v5
	v_rcp_f32_e32 v28, v5
	v_pk_mul_f32 v[30:31], v[138:139], v[4:5] op_sel_hi:[1,0]
	v_and_b32_e32 v5, 0xffff0000, v12
	v_mul_f32_e32 v5, 0xbfb8aa3b, v5
	v_exp_f32_e32 v5, v5
	s_waitcnt lgkmcnt(1)
	v_pk_mul_f32 v[0:1], v[0:1], v[30:31]
	v_add_f32_e32 v5, 1.0, v5
	v_rcp_f32_e32 v29, v5
	v_lshlrev_b32_e32 v5, 16, v13
	v_mul_f32_e32 v5, 0xbfb8aa3b, v5
	v_exp_f32_e32 v5, v5
	v_pk_mul_f32 v[0:1], v[28:29], v[0:1]
	v_add_f32_e32 v5, 1.0, v5
	v_rcp_f32_e32 v12, v5
	v_pk_mul_f32 v[28:29], v[134:135], v[4:5] op_sel_hi:[1,0]
	v_and_b32_e32 v5, 0xffff0000, v13
	v_mul_f32_e32 v5, 0xbfb8aa3b, v5
	v_exp_f32_e32 v5, v5
	v_pk_mul_f32 v[2:3], v[2:3], v[28:29]
	v_cvt_pk_bf16_f32 v0, v0, v1
	v_add_f32_e32 v5, 1.0, v5
	v_rcp_f32_e32 v13, v5
	s_nop 0
	v_pk_mul_f32 v[2:3], v[12:13], v[2:3]
	s_nop 0
	v_cvt_pk_bf16_f32 v1, v2, v3
	global_store_dwordx2 v[70:71], v[0:1], off offset:64
	v_mov_b32_e32 v0, v170
	v_mov_b32_e32 v1, v171
	v_pk_mul_f32 v[12:13], v[118:119], v[4:5] op_sel_hi:[1,0]
	v_lshlrev_b32_e32 v2, 16, v0
	v_and_b32_e32 v0, 0xffff0000, v0
	v_mul_f32_e32 v0, 0xbfb8aa3b, v0
	v_exp_f32_e32 v0, v0
	v_mul_f32_e32 v2, 0xbfb8aa3b, v2
	v_exp_f32_e32 v2, v2
	s_waitcnt lgkmcnt(0)
	v_pk_mul_f32 v[8:9], v[8:9], v[12:13]
	v_add_f32_e32 v0, 1.0, v0
	v_rcp_f32_e32 v3, v0
	v_lshlrev_b32_e32 v0, 16, v1
	v_and_b32_e32 v1, 0xffff0000, v1
	v_mul_f32_e32 v0, 0xbfb8aa3b, v0
	v_mul_f32_e32 v1, 0xbfb8aa3b, v1
	v_exp_f32_e32 v0, v0
	v_exp_f32_e32 v1, v1
	v_add_f32_e32 v2, 1.0, v2
	v_rcp_f32_e32 v2, v2
	v_add_f32_e32 v0, 1.0, v0
	v_add_f32_e32 v1, 1.0, v1
	v_rcp_f32_e32 v0, v0
	v_rcp_f32_e32 v1, v1
	v_pk_mul_f32 v[2:3], v[2:3], v[8:9]
	v_pk_mul_f32 v[8:9], v[116:117], v[4:5] op_sel_hi:[1,0]
	v_cvt_pk_bf16_f32 v2, v2, v3
	v_pk_mul_f32 v[8:9], v[10:11], v[8:9]
	s_nop 0
	v_pk_mul_f32 v[0:1], v[0:1], v[8:9]
	v_mov_b32_e32 v8, v172
	v_mov_b32_e32 v9, v173
	v_cvt_pk_bf16_f32 v3, v0, v1
	global_store_dwordx2 v[70:71], v[2:3], off offset:80
	ds_read_b128 v[0:3], v81 offset:20672
	v_lshlrev_b32_e32 v5, 16, v8
	v_mul_f32_e32 v5, 0xbfb8aa3b, v5
	v_exp_f32_e32 v5, v5
	s_nop 0
	v_add_f32_e32 v5, 1.0, v5
	v_rcp_f32_e32 v10, v5
	v_pk_mul_f32 v[12:13], v[62:63], v[4:5] op_sel_hi:[1,0]
	v_and_b32_e32 v5, 0xffff0000, v8
	v_mul_f32_e32 v5, 0xbfb8aa3b, v5
	v_exp_f32_e32 v5, v5
	s_waitcnt lgkmcnt(0)
	v_pk_mul_f32 v[0:1], v[0:1], v[12:13]
	v_add_f32_e32 v5, 1.0, v5
	v_rcp_f32_e32 v11, v5
	v_lshlrev_b32_e32 v5, 16, v9
	v_mul_f32_e32 v5, 0xbfb8aa3b, v5
	v_exp_f32_e32 v5, v5
	v_pk_mul_f32 v[0:1], v[10:11], v[0:1]
	v_add_f32_e32 v5, 1.0, v5
	v_rcp_f32_e32 v8, v5
	v_pk_mul_f32 v[10:11], v[60:61], v[4:5] op_sel_hi:[1,0]
	v_and_b32_e32 v5, 0xffff0000, v9
	v_mul_f32_e32 v5, 0xbfb8aa3b, v5
	v_exp_f32_e32 v5, v5
	v_pk_mul_f32 v[2:3], v[2:3], v[10:11]
	v_cvt_pk_bf16_f32 v0, v0, v1
	v_add_f32_e32 v5, 1.0, v5
	v_rcp_f32_e32 v9, v5
	s_nop 0
	v_pk_mul_f32 v[2:3], v[8:9], v[2:3]
	v_mov_b32_e32 v8, v174
	v_mov_b32_e32 v9, v175
	v_cvt_pk_bf16_f32 v1, v2, v3
	global_store_dwordx2 v[70:71], v[0:1], off offset:96
	ds_read_b128 v[0:3], v81 offset:20704
	v_lshlrev_b32_e32 v5, 16, v8
	v_mul_f32_e32 v5, 0xbfb8aa3b, v5
	v_exp_f32_e32 v5, v5
	s_nop 0
	v_add_f32_e32 v5, 1.0, v5
	v_rcp_f32_e32 v10, v5
	v_pk_mul_f32 v[12:13], v[44:45], v[4:5] op_sel_hi:[1,0]
	v_and_b32_e32 v5, 0xffff0000, v8
	v_mul_f32_e32 v5, 0xbfb8aa3b, v5
	v_exp_f32_e32 v5, v5
	s_waitcnt lgkmcnt(0)
	v_pk_mul_f32 v[0:1], v[0:1], v[12:13]
	v_add_f32_e32 v5, 1.0, v5
	v_rcp_f32_e32 v11, v5
	v_lshlrev_b32_e32 v5, 16, v9
	v_mul_f32_e32 v5, 0xbfb8aa3b, v5
	v_exp_f32_e32 v5, v5
	v_pk_mul_f32 v[0:1], v[10:11], v[0:1]
	v_add_f32_e32 v5, 1.0, v5
	v_rcp_f32_e32 v8, v5
	v_pk_mul_f32 v[10:11], v[46:47], v[4:5] op_sel_hi:[1,0]
	v_and_b32_e32 v5, 0xffff0000, v9
	v_mul_f32_e32 v5, 0xbfb8aa3b, v5
	v_exp_f32_e32 v5, v5
	v_pk_mul_f32 v[2:3], v[2:3], v[10:11]
	v_cvt_pk_bf16_f32 v0, v0, v1
	v_add_f32_e32 v5, 1.0, v5
	v_rcp_f32_e32 v9, v5
	s_nop 0
	v_pk_mul_f32 v[2:3], v[8:9], v[2:3]
	s_nop 0
	v_cvt_pk_bf16_f32 v1, v2, v3
	global_store_dwordx2 v[70:71], v[0:1], off offset:112
	v_mov_b32_e32 v12, v176
	v_mov_b32_e32 v13, v177
	ds_read_b128 v[0:3], v81 offset:20736
	ds_read_b128 v[8:11], v81 offset:20768
	v_lshlrev_b32_e32 v5, 16, v12
	v_mul_f32_e32 v5, 0xbfb8aa3b, v5
	v_exp_f32_e32 v5, v5
	s_nop 0
	v_add_f32_e32 v5, 1.0, v5
	v_rcp_f32_e32 v28, v5
	v_pk_mul_f32 v[30:31], v[42:43], v[4:5] op_sel_hi:[1,0]
	v_and_b32_e32 v5, 0xffff0000, v12
	v_mul_f32_e32 v5, 0xbfb8aa3b, v5
	v_exp_f32_e32 v5, v5
	s_waitcnt lgkmcnt(1)
; #define LAS __attribute__((address_space(3)))
; __device__ __forceinline__ unsigned pk2(float lo, float hi) { f32x2_t v = {lo, hi}; bf16x2_t b = __builtin_convertvector(v, bf16x2_t); return __builtin_bit_cast(unsigned, b); }
; __device__ __forceinline__ float bflo(unsigned w) { return __uint_as_float(w << 16); }
; __device__ __forceinline__ float bfhi(unsigned w) { return __uint_as_float(w & 0xffff0000u); }
; __device__ __forceinline__ float sigmoidf_(float x) { return __builtin_amdgcn_rcpf(1.f + fexp(-x)); }
; template <bool SAMPLE>
; __device__ __forceinline__ void mout_task(Ctx& C, int l, int unit, int h, int tb, const LAS float* cwl, const LAS float* gainl, LAS float* gsbuf, LAS s16x8* qfl, const bool st) {
;     ...
; #pragma unroll
;     for (int vb = 0; vb < 4; ++vb)
; #pragma unroll
;         for (int i4 = 0; i4 < 4; ++i4) { const int v0 = 32 * vb + 8 * i4 + 4 * hi2;
;             const u32x2 ow = *(const u32x2*)(orow + v0); const f32x4 gn = *(const LAS f32x4*)(gainl + h * 128 + v0);
;             const float y0 = acc[vb][4 * i4] * rn * gn[0] * sigmoidf_(bflo(ow.x)), y1 = acc[vb][4 * i4 + 1] * rn * gn[1] * sigmoidf_(bfhi(ow.x));
;             const float y2 = acc[vb][4 * i4 + 2] * rn * gn[2] * sigmoidf_(bflo(ow.y)), y3 = acc[vb][4 * i4 + 3] * rn * gn[3] * sigmoidf_(bfhi(ow.y));
;             u32x2 w; w.x = pk2(y0, y1); w.y = pk2(y2, y3); if (st) *(u32x2*)(orow + v0) = w; if (i4 == 3) asm volatile("" ::: "memory"); }
	v_pk_mul_f32 v[0:1], v[0:1], v[30:31]
	v_add_f32_e32 v5, 1.0, v5
	v_rcp_f32_e32 v29, v5
	v_lshlrev_b32_e32 v5, 16, v13
	v_mul_f32_e32 v5, 0xbfb8aa3b, v5
	v_exp_f32_e32 v5, v5
	v_pk_mul_f32 v[0:1], v[28:29], v[0:1]
	v_add_f32_e32 v5, 1.0, v5
	v_rcp_f32_e32 v12, v5
	v_pk_mul_f32 v[28:29], v[40:41], v[4:5] op_sel_hi:[1,0]
	v_and_b32_e32 v5, 0xffff0000, v13
	v_mul_f32_e32 v5, 0xbfb8aa3b, v5
	v_exp_f32_e32 v5, v5
	v_pk_mul_f32 v[2:3], v[2:3], v[28:29]
	v_cvt_pk_bf16_f32 v0, v0, v1
	v_add_f32_e32 v5, 1.0, v5
	v_rcp_f32_e32 v13, v5
	s_nop 0
	v_pk_mul_f32 v[2:3], v[12:13], v[2:3]
	s_nop 0
	v_cvt_pk_bf16_f32 v1, v2, v3
	global_store_dwordx2 v[70:71], v[0:1], off offset:128
	v_mov_b32_e32 v0, v180
	v_mov_b32_e32 v1, v181
	v_pk_mul_f32 v[12:13], v[38:39], v[4:5] op_sel_hi:[1,0]
	v_lshlrev_b32_e32 v2, 16, v0
	v_and_b32_e32 v0, 0xffff0000, v0
	v_mul_f32_e32 v0, 0xbfb8aa3b, v0
	v_exp_f32_e32 v0, v0
	v_mul_f32_e32 v2, 0xbfb8aa3b, v2
	v_exp_f32_e32 v2, v2
	s_waitcnt lgkmcnt(0)
	v_pk_mul_f32 v[8:9], v[8:9], v[12:13]
	v_add_f32_e32 v0, 1.0, v0
	v_rcp_f32_e32 v3, v0
	v_lshlrev_b32_e32 v0, 16, v1
	v_and_b32_e32 v1, 0xffff0000, v1
	v_mul_f32_e32 v0, 0xbfb8aa3b, v0
	v_mul_f32_e32 v1, 0xbfb8aa3b, v1
	v_exp_f32_e32 v0, v0
	v_exp_f32_e32 v1, v1
	v_add_f32_e32 v2, 1.0, v2
	v_rcp_f32_e32 v2, v2
	v_add_f32_e32 v0, 1.0, v0
	v_add_f32_e32 v1, 1.0, v1
	v_rcp_f32_e32 v0, v0
	v_rcp_f32_e32 v1, v1
	v_pk_mul_f32 v[2:3], v[2:3], v[8:9]
	v_pk_mul_f32 v[8:9], v[36:37], v[4:5] op_sel_hi:[1,0]
	v_cvt_pk_bf16_f32 v2, v2, v3
	v_pk_mul_f32 v[8:9], v[10:11], v[8:9]
	s_nop 0
	v_pk_mul_f32 v[0:1], v[0:1], v[8:9]
	v_mov_b32_e32 v8, v182
	v_mov_b32_e32 v9, v183
	v_cvt_pk_bf16_f32 v3, v0, v1
	global_store_dwordx2 v[70:71], v[2:3], off offset:144
	ds_read_b128 v[0:3], v81 offset:20800
	v_lshlrev_b32_e32 v5, 16, v8
	v_mul_f32_e32 v5, 0xbfb8aa3b, v5
	v_exp_f32_e32 v5, v5
	s_nop 0
	v_add_f32_e32 v5, 1.0, v5
	v_rcp_f32_e32 v10, v5
	v_pk_mul_f32 v[12:13], v[34:35], v[4:5] op_sel_hi:[1,0]
	v_and_b32_e32 v5, 0xffff0000, v8
	v_mul_f32_e32 v5, 0xbfb8aa3b, v5
	v_exp_f32_e32 v5, v5
	s_waitcnt lgkmcnt(0)
	v_pk_mul_f32 v[0:1], v[0:1], v[12:13]
	v_add_f32_e32 v5, 1.0, v5
	v_rcp_f32_e32 v11, v5
	v_lshlrev_b32_e32 v5, 16, v9
	v_mul_f32_e32 v5, 0xbfb8aa3b, v5
	v_exp_f32_e32 v5, v5
	v_pk_mul_f32 v[0:1], v[10:11], v[0:1]
	v_add_f32_e32 v5, 1.0, v5
	v_rcp_f32_e32 v8, v5
	v_pk_mul_f32 v[10:11], v[32:33], v[4:5] op_sel_hi:[1,0]
	v_and_b32_e32 v5, 0xffff0000, v9
	v_mul_f32_e32 v5, 0xbfb8aa3b, v5
	v_exp_f32_e32 v5, v5
	v_pk_mul_f32 v[2:3], v[2:3], v[10:11]
	v_cvt_pk_bf16_f32 v0, v0, v1
	v_add_f32_e32 v5, 1.0, v5
	v_rcp_f32_e32 v9, v5
	s_nop 0
	v_pk_mul_f32 v[2:3], v[8:9], v[2:3]
	v_mov_b32_e32 v8, v186
	v_mov_b32_e32 v9, v187
	v_cvt_pk_bf16_f32 v1, v2, v3
	global_store_dwordx2 v[70:71], v[0:1], off offset:160
	ds_read_b128 v[0:3], v81 offset:20832
	v_lshlrev_b32_e32 v5, 16, v8
	v_mul_f32_e32 v5, 0xbfb8aa3b, v5
	v_exp_f32_e32 v5, v5
	s_nop 0
	v_add_f32_e32 v5, 1.0, v5
	v_rcp_f32_e32 v10, v5
	v_pk_mul_f32 v[12:13], v[26:27], v[4:5] op_sel_hi:[1,0]
	v_and_b32_e32 v5, 0xffff0000, v8
	v_mul_f32_e32 v5, 0xbfb8aa3b, v5
	v_exp_f32_e32 v5, v5
	s_waitcnt lgkmcnt(0)
	v_pk_mul_f32 v[0:1], v[0:1], v[12:13]
	v_add_f32_e32 v5, 1.0, v5
	v_rcp_f32_e32 v11, v5
	v_lshlrev_b32_e32 v5, 16, v9
	v_mul_f32_e32 v5, 0xbfb8aa3b, v5
	v_exp_f32_e32 v5, v5
	v_pk_mul_f32 v[0:1], v[10:11], v[0:1]
	v_add_f32_e32 v5, 1.0, v5
	v_rcp_f32_e32 v8, v5
	v_pk_mul_f32 v[10:11], v[24:25], v[4:5] op_sel_hi:[1,0]
	v_and_b32_e32 v5, 0xffff0000, v9
	v_mul_f32_e32 v5, 0xbfb8aa3b, v5
	v_exp_f32_e32 v5, v5
	v_pk_mul_f32 v[2:3], v[2:3], v[10:11]
	v_cvt_pk_bf16_f32 v0, v0, v1
	v_add_f32_e32 v5, 1.0, v5
	v_rcp_f32_e32 v9, v5
	s_nop 0
	v_pk_mul_f32 v[2:3], v[8:9], v[2:3]
	s_nop 0
	v_cvt_pk_bf16_f32 v1, v2, v3
	global_store_dwordx2 v[70:71], v[0:1], off offset:176
	v_mov_b32_e32 v12, v194
	v_mov_b32_e32 v13, v195
	ds_read_b128 v[0:3], v81 offset:20864
	ds_read_b128 v[8:11], v81 offset:20896
	v_lshlrev_b32_e32 v5, 16, v12
	v_mul_f32_e32 v5, 0xbfb8aa3b, v5
	v_exp_f32_e32 v5, v5
	s_nop 0
	v_add_f32_e32 v5, 1.0, v5
	v_rcp_f32_e32 v24, v5
	v_pk_mul_f32 v[22:23], v[22:23], v[4:5] op_sel_hi:[1,0]
	v_and_b32_e32 v5, 0xffff0000, v12
	v_mul_f32_e32 v5, 0xbfb8aa3b, v5
	v_exp_f32_e32 v5, v5
	s_waitcnt lgkmcnt(1)
; #define LAS __attribute__((address_space(3)))
; __device__ __forceinline__ unsigned pk2(float lo, float hi) { f32x2_t v = {lo, hi}; bf16x2_t b = __builtin_convertvector(v, bf16x2_t); return __builtin_bit_cast(unsigned, b); }
; __device__ __forceinline__ float bflo(unsigned w) { return __uint_as_float(w << 16); }
; __device__ __forceinline__ float bfhi(unsigned w) { return __uint_as_float(w & 0xffff0000u); }
; __device__ __forceinline__ float sigmoidf_(float x) { return __builtin_amdgcn_rcpf(1.f + fexp(-x)); }
; #define LDS_WAIT() asm volatile("s_waitcnt lgkmcnt(0)" ::: "memory")
; template <bool SAMPLE>
; __device__ __forceinline__ void mout_task(Ctx& C, int l, int unit, int h, int tb, const LAS float* cwl, const LAS float* gainl, LAS float* gsbuf, LAS s16x8* qfl, const bool st) {
;     ...
; #pragma unroll
;     for (int vb = 0; vb < 4; ++vb)
; #pragma unroll
;         for (int i4 = 0; i4 < 4; ++i4) { const int v0 = 32 * vb + 8 * i4 + 4 * hi2;
;             const u32x2 ow = *(const u32x2*)(orow + v0); const f32x4 gn = *(const LAS f32x4*)(gainl + h * 128 + v0);
;             const float y0 = acc[vb][4 * i4] * rn * gn[0] * sigmoidf_(bflo(ow.x)), y1 = acc[vb][4 * i4 + 1] * rn * gn[1] * sigmoidf_(bfhi(ow.x));
;             const float y2 = acc[vb][4 * i4 + 2] * rn * gn[2] * sigmoidf_(bflo(ow.y)), y3 = acc[vb][4 * i4 + 3] * rn * gn[3] * sigmoidf_(bfhi(ow.y));
;             u32x2 w; w.x = pk2(y0, y1); w.y = pk2(y2, y3); if (st) *(u32x2*)(orow + v0) = w; if (i4 == 3) asm volatile("" ::: "memory"); }
;     LDS_WAIT();
	v_pk_mul_f32 v[0:1], v[0:1], v[22:23]
	v_add_f32_e32 v5, 1.0, v5
	v_rcp_f32_e32 v25, v5
	v_lshlrev_b32_e32 v5, 16, v13
	v_mul_f32_e32 v5, 0xbfb8aa3b, v5
	v_exp_f32_e32 v5, v5
	v_pk_mul_f32 v[0:1], v[24:25], v[0:1]
	v_add_f32_e32 v5, 1.0, v5
	v_rcp_f32_e32 v12, v5
	v_pk_mul_f32 v[20:21], v[20:21], v[4:5] op_sel_hi:[1,0]
	v_and_b32_e32 v5, 0xffff0000, v13
	v_mul_f32_e32 v5, 0xbfb8aa3b, v5
	v_exp_f32_e32 v5, v5
	v_pk_mul_f32 v[2:3], v[2:3], v[20:21]
	v_cvt_pk_bf16_f32 v0, v0, v1
	v_add_f32_e32 v5, 1.0, v5
	v_rcp_f32_e32 v13, v5
	s_nop 0
	v_pk_mul_f32 v[2:3], v[12:13], v[2:3]
	s_nop 0
	v_cvt_pk_bf16_f32 v1, v2, v3
	global_store_dwordx2 v[70:71], v[0:1], off offset:192
	v_mov_b32_e32 v0, v196
	v_mov_b32_e32 v1, v197
	v_pk_mul_f32 v[12:13], v[18:19], v[4:5] op_sel_hi:[1,0]
	v_lshlrev_b32_e32 v2, 16, v0
	v_and_b32_e32 v0, 0xffff0000, v0
	v_mul_f32_e32 v0, 0xbfb8aa3b, v0
	v_exp_f32_e32 v0, v0
	v_mul_f32_e32 v2, 0xbfb8aa3b, v2
	v_exp_f32_e32 v2, v2
	s_waitcnt lgkmcnt(0)
	v_pk_mul_f32 v[8:9], v[8:9], v[12:13]
	v_add_f32_e32 v0, 1.0, v0
	v_rcp_f32_e32 v3, v0
	v_lshlrev_b32_e32 v0, 16, v1
	v_and_b32_e32 v1, 0xffff0000, v1
	v_mul_f32_e32 v0, 0xbfb8aa3b, v0
	v_mul_f32_e32 v1, 0xbfb8aa3b, v1
	v_exp_f32_e32 v0, v0
	v_exp_f32_e32 v1, v1
	v_add_f32_e32 v2, 1.0, v2
	v_rcp_f32_e32 v2, v2
	v_add_f32_e32 v0, 1.0, v0
	v_add_f32_e32 v1, 1.0, v1
	v_rcp_f32_e32 v0, v0
	v_rcp_f32_e32 v1, v1
	v_pk_mul_f32 v[2:3], v[2:3], v[8:9]
	v_pk_mul_f32 v[8:9], v[16:17], v[4:5] op_sel_hi:[1,0]
	v_cvt_pk_bf16_f32 v2, v2, v3
	v_pk_mul_f32 v[8:9], v[10:11], v[8:9]
	s_nop 0
	v_pk_mul_f32 v[0:1], v[0:1], v[8:9]
	v_mov_b32_e32 v8, v198
	v_mov_b32_e32 v9, v199
	v_cvt_pk_bf16_f32 v3, v0, v1
	global_store_dwordx2 v[70:71], v[2:3], off offset:208
	ds_read_b128 v[0:3], v81 offset:20928
	v_lshlrev_b32_e32 v5, 16, v8
	v_mul_f32_e32 v5, 0xbfb8aa3b, v5
	v_exp_f32_e32 v5, v5
	s_nop 0
	v_add_f32_e32 v5, 1.0, v5
	v_rcp_f32_e32 v10, v5
	v_pk_mul_f32 v[6:7], v[6:7], v[4:5] op_sel_hi:[1,0]
	v_and_b32_e32 v5, 0xffff0000, v8
	v_mul_f32_e32 v5, 0xbfb8aa3b, v5
	v_exp_f32_e32 v5, v5
	s_waitcnt lgkmcnt(0)
	v_pk_mul_f32 v[0:1], v[0:1], v[6:7]
	v_add_f32_e32 v5, 1.0, v5
	v_rcp_f32_e32 v11, v5
	v_lshlrev_b32_e32 v5, 16, v9
	v_mul_f32_e32 v5, 0xbfb8aa3b, v5
	v_exp_f32_e32 v5, v5
	v_pk_mul_f32 v[0:1], v[10:11], v[0:1]
	v_add_f32_e32 v5, 1.0, v5
	v_rcp_f32_e32 v6, v5
	v_and_b32_e32 v5, 0xffff0000, v9
	v_mul_f32_e32 v5, 0xbfb8aa3b, v5
	v_exp_f32_e32 v5, v5
	v_cvt_pk_bf16_f32 v0, v0, v1
	v_add_f32_e32 v5, 1.0, v5
	v_rcp_f32_e32 v7, v5
	v_pk_mul_f32 v[8:9], v[72:73], v[4:5] op_sel_hi:[1,0]
	s_nop 0
	v_pk_mul_f32 v[2:3], v[2:3], v[8:9]
	s_nop 0
	v_pk_mul_f32 v[2:3], v[6:7], v[2:3]
	v_mov_b32_e32 v6, v214
	v_mov_b32_e32 v7, v215
	v_cvt_pk_bf16_f32 v1, v2, v3
	global_store_dwordx2 v[70:71], v[0:1], off offset:224
	ds_read_b128 v[0:3], v81 offset:20960
	v_lshlrev_b32_e32 v5, 16, v6
	v_mul_f32_e32 v5, 0xbfb8aa3b, v5
	v_exp_f32_e32 v5, v5
	s_nop 0
	v_add_f32_e32 v5, 1.0, v5
	v_rcp_f32_e32 v8, v5
	v_and_b32_e32 v5, 0xffff0000, v6
	v_mul_f32_e32 v5, 0xbfb8aa3b, v5
	v_exp_f32_e32 v5, v5
	s_nop 0
	v_add_f32_e32 v5, 1.0, v5
	v_rcp_f32_e32 v9, v5
	v_pk_mul_f32 v[10:11], v[68:69], v[4:5] op_sel_hi:[1,0]
	v_lshlrev_b32_e32 v5, 16, v7
	v_mul_f32_e32 v5, 0xbfb8aa3b, v5
	v_exp_f32_e32 v5, v5
	s_waitcnt lgkmcnt(0)
	v_pk_mul_f32 v[0:1], v[0:1], v[10:11]
	v_add_f32_e32 v5, 1.0, v5
	v_rcp_f32_e32 v6, v5
	v_and_b32_e32 v5, 0xffff0000, v7
	v_mul_f32_e32 v5, 0xbfb8aa3b, v5
	v_exp_f32_e32 v5, v5
	v_pk_mul_f32 v[0:1], v[8:9], v[0:1]
	v_add_f32_e32 v5, 1.0, v5
	v_rcp_f32_e32 v7, v5
	v_pk_mul_f32 v[4:5], v[14:15], v[4:5] op_sel_hi:[1,0]
	v_cvt_pk_bf16_f32 v0, v0, v1
	v_pk_mul_f32 v[2:3], v[2:3], v[4:5]
	s_nop 0
	v_pk_mul_f32 v[2:3], v[6:7], v[2:3]
	s_nop 0
	v_cvt_pk_bf16_f32 v1, v2, v3
	global_store_dwordx2 v[70:71], v[0:1], off offset:240
	s_waitcnt lgkmcnt(0)
	s_branch .LBB0_903
